# attention unit epilogues (GQA, neighbourhood latent + context): the four z row loads of the gate issued together with counted waits; add/pack interleave also in neighbourhood loop and tail loops
# speedup vs baseline: 1.0562x; 1.0047x over previous
.LBB0_276:
	v_add_u32_e32 v0, s46, v251
	ds_read_b64_tr_b16 v[198:199], v0 offset:24576
	ds_read_b64_tr_b16 v[200:201], v0 offset:25088
	s_waitcnt lgkmcnt(9)
	v_mfma_f32_32x32x16_bf16 v[114:129], v[194:197], v[162:165], 0
	v_add_f32_e32 v2, v98, v99
	v_cvt_pk_bf16_f32 v150, v98, v99
	v_add_f32_e32 v2, v100, v2
	v_cvt_pk_bf16_f32 v151, v100, v101
	v_add_f32_e32 v2, v101, v2
	v_add_f32_e32 v2, v102, v2
	v_add_f32_e32 v2, v103, v2
	ds_read_b64_tr_b16 v[194:195], v0 offset:28672
	ds_read_b64_tr_b16 v[196:197], v0 offset:29184
	s_waitcnt lgkmcnt(10)
	v_mfma_f32_32x32x16_bf16 v[130:145], v[186:189], v[162:165], 0
	v_add_f32_e32 v2, v104, v2
	v_cvt_pk_bf16_f32 v152, v102, v103
	v_add_f32_e32 v2, v105, v2
	v_cvt_pk_bf16_f32 v153, v104, v105
	v_add_f32_e32 v2, v106, v2
	v_add_f32_e32 v2, v107, v2
	ds_read_b64_tr_b16 v[162:163], v0 offset:25600
	ds_read_b64_tr_b16 v[164:165], v0 offset:26112
	s_waitcnt lgkmcnt(11)
	v_mfma_f32_32x32x16_bf16 v[114:129], v[190:193], v[158:161], v[114:129]
	v_add_f32_e32 v2, v108, v2
	v_cvt_pk_bf16_f32 v10, v106, v107
	v_add_f32_e32 v2, v109, v2
	v_cvt_pk_bf16_f32 v11, v108, v109
	v_add_f32_e32 v2, v110, v2
	v_add_f32_e32 v2, v111, v2
	ds_read_b64_tr_b16 v[106:107], v0 offset:29696
	ds_read_b64_tr_b16 v[108:109], v0 offset:30208
	s_waitcnt lgkmcnt(12)
	v_mfma_f32_32x32x16_bf16 v[130:145], v[182:185], v[158:161], v[130:145]
	v_add_f32_e32 v2, v112, v2
	v_cvt_pk_bf16_f32 v12, v110, v111
	v_add_f32_e32 v2, v113, v2
	v_cvt_pk_bf16_f32 v13, v112, v113
	v_add_f32_e32 v2, v82, v2
	v_add_f32_e32 v2, v83, v2
	ds_read_b64_tr_b16 v[102:103], v0 offset:26624
	ds_read_b64_tr_b16 v[104:105], v0 offset:27136
	s_waitcnt lgkmcnt(13)
	v_mfma_f32_32x32x16_bf16 v[114:129], v[178:181], v[154:157], v[114:129]
	v_add_f32_e32 v2, v84, v2
	v_cvt_pk_bf16_f32 v6, v82, v83
	v_add_f32_e32 v2, v85, v2
	v_cvt_pk_bf16_f32 v7, v84, v85
	v_add_f32_e32 v2, v86, v2
	v_add_f32_e32 v2, v87, v2
	ds_read_b64_tr_b16 v[98:99], v0 offset:30720
	ds_read_b64_tr_b16 v[100:101], v0 offset:31232
	s_waitcnt lgkmcnt(14)
	v_mfma_f32_32x32x16_bf16 v[130:145], v[174:177], v[154:157], v[130:145]
	v_add_f32_e32 v2, v88, v2
	v_cvt_pk_bf16_f32 v8, v86, v87
	v_add_f32_e32 v2, v89, v2
	v_cvt_pk_bf16_f32 v9, v88, v89
	v_add_f32_e32 v2, v90, v2
	v_add_f32_e32 v2, v91, v2
	ds_read_b64_tr_b16 v[86:87], v0 offset:27648
	ds_read_b64_tr_b16 v[88:89], v0 offset:28160
	s_waitcnt lgkmcnt(14)
	v_mfma_f32_32x32x16_bf16 v[114:129], v[170:173], v[146:149], v[114:129]
	v_add_f32_e32 v2, v92, v2
	v_cvt_pk_bf16_f32 v3, v92, v93
	v_add_f32_e32 v2, v93, v2
	v_add_f32_e32 v2, v94, v2
	v_add_f32_e32 v14, v95, v2
	v_cvt_pk_bf16_f32 v2, v90, v91
	ds_read_b64_tr_b16 v[82:83], v0 offset:31744
	ds_read_b64_tr_b16 v[84:85], v0 offset:32256
	v_mfma_f32_32x32x16_bf16 v[130:145], v[166:169], v[146:149], v[130:145]
	v_add_f32_e32 v0, v96, v14
	v_cvt_pk_bf16_f32 v4, v94, v95
	v_add_f32_e32 v0, v97, v0
	v_cvt_pk_bf16_f32 v5, v96, v97
	v_add_f32_e32 v0, 0, v0
	v_max_f32_e32 v14, v115, v115
	v_max_f32_e32 v15, v114, v114
	v_max_f32_e32 v14, v15, v14
	s_nop 3
	v_max3_f32 v15, v116, v117, v131
	v_max3_f32 v14, v14, v130, v132
	v_max3_f32 v14, v14, v133, v118
	v_max3_f32 v15, v15, v120, v121
	v_max3_f32 v14, v14, v119, v134
	v_max3_f32 v15, v15, v136, v137
	v_max3_f32 v14, v14, v135, v122
	v_max3_f32 v15, v15, v124, v125
	v_max3_f32 v14, v14, v123, v138
	v_max3_f32 v15, v15, v140, v141
	v_max3_f32 v14, v14, v139, v126
	v_max3_f32 v15, v15, v128, v129
	v_max3_f32 v14, v14, v127, v142
	v_max3_f32 v15, v15, v144, v145
	v_max3_f32 v14, v14, v143, v15
	v_mov_b32_e32 v15, v14
	s_nop 1
	v_permlane32_swap_b32_e32 v14, v15
	v_max_f32_e32 v15, v15, v15
	v_max_f32_e32 v14, v14, v14
	v_max_f32_e32 v14, v14, v15
	v_sub_f32_e32 v14, v14, v248
	v_cmp_lt_f32_e32 vcc, s84, v14
	s_cmp_lg_u64 vcc, 0
	v_add_f32_e32 v0, v232, v0
	s_cselect_b64 s[6:7], -1, 0
	s_cbranch_vccnz .LBB0_327

.LBB0_283:
	v_add_u32_e32 v0, s13, v251
	ds_read_b64_tr_b16 v[198:199], v0 offset:24576
	ds_read_b64_tr_b16 v[200:201], v0 offset:25088
	s_waitcnt lgkmcnt(9)
	v_mfma_f32_32x32x16_bf16 v[130:145], v[194:197], v[162:165], 0
	v_add_f32_e32 v2, v98, v99
	v_cvt_pk_bf16_f32 v150, v98, v99
	v_add_f32_e32 v2, v100, v2
	v_cvt_pk_bf16_f32 v151, v100, v101
	v_add_f32_e32 v2, v101, v2
	v_add_f32_e32 v2, v102, v2
	v_add_f32_e32 v2, v103, v2
	ds_read_b64_tr_b16 v[194:195], v0 offset:28672
	ds_read_b64_tr_b16 v[196:197], v0 offset:29184
	s_waitcnt lgkmcnt(10)
	v_mfma_f32_32x32x16_bf16 v[114:129], v[186:189], v[162:165], 0
	v_add_f32_e32 v2, v104, v2
	v_cvt_pk_bf16_f32 v152, v102, v103
	v_add_f32_e32 v2, v105, v2
	v_cvt_pk_bf16_f32 v153, v104, v105
	v_add_f32_e32 v2, v106, v2
	v_add_f32_e32 v2, v107, v2
	ds_read_b64_tr_b16 v[186:187], v0 offset:25600
	ds_read_b64_tr_b16 v[188:189], v0 offset:26112
	s_waitcnt lgkmcnt(11)
	v_mfma_f32_32x32x16_bf16 v[130:145], v[190:193], v[158:161], v[130:145]
	v_add_f32_e32 v2, v108, v2
	v_cvt_pk_bf16_f32 v10, v106, v107
	v_add_f32_e32 v2, v109, v2
	v_cvt_pk_bf16_f32 v11, v108, v109
	v_add_f32_e32 v2, v110, v2
	v_add_f32_e32 v2, v111, v2
	ds_read_b64_tr_b16 v[106:107], v0 offset:29696
	ds_read_b64_tr_b16 v[108:109], v0 offset:30208
	s_waitcnt lgkmcnt(12)
	v_mfma_f32_32x32x16_bf16 v[114:129], v[182:185], v[158:161], v[114:129]
	v_add_f32_e32 v2, v112, v2
	v_cvt_pk_bf16_f32 v12, v110, v111
	v_add_f32_e32 v2, v113, v2
	v_cvt_pk_bf16_f32 v13, v112, v113
	v_add_f32_e32 v2, v82, v2
	v_add_f32_e32 v2, v83, v2
	ds_read_b64_tr_b16 v[102:103], v0 offset:26624
	ds_read_b64_tr_b16 v[104:105], v0 offset:27136
	s_waitcnt lgkmcnt(13)
	v_mfma_f32_32x32x16_bf16 v[130:145], v[178:181], v[154:157], v[130:145]
	v_add_f32_e32 v2, v84, v2
	v_cvt_pk_bf16_f32 v6, v82, v83
	v_add_f32_e32 v2, v85, v2
	v_cvt_pk_bf16_f32 v7, v84, v85
	v_add_f32_e32 v2, v86, v2
	v_add_f32_e32 v2, v87, v2
	ds_read_b64_tr_b16 v[98:99], v0 offset:30720
	ds_read_b64_tr_b16 v[100:101], v0 offset:31232
	s_waitcnt lgkmcnt(14)
	v_mfma_f32_32x32x16_bf16 v[114:129], v[174:177], v[154:157], v[114:129]
	v_add_f32_e32 v2, v88, v2
	v_cvt_pk_bf16_f32 v8, v86, v87
	v_add_f32_e32 v2, v89, v2
	v_cvt_pk_bf16_f32 v9, v88, v89
	v_add_f32_e32 v2, v90, v2
	v_add_f32_e32 v2, v91, v2
	ds_read_b64_tr_b16 v[82:83], v0 offset:27648
	ds_read_b64_tr_b16 v[84:85], v0 offset:28160
	s_waitcnt lgkmcnt(14)
	v_mfma_f32_32x32x16_bf16 v[130:145], v[170:173], v[146:149], v[130:145]
	v_add_f32_e32 v2, v92, v2
	v_cvt_pk_bf16_f32 v3, v92, v93
	v_add_f32_e32 v2, v93, v2
	v_add_f32_e32 v2, v94, v2
	v_add_f32_e32 v14, v95, v2
	v_cvt_pk_bf16_f32 v2, v90, v91
	ds_read_b64_tr_b16 v[86:87], v0 offset:31744
	ds_read_b64_tr_b16 v[88:89], v0 offset:32256
	v_mfma_f32_32x32x16_bf16 v[114:129], v[166:169], v[146:149], v[114:129]
	v_add_f32_e32 v0, v96, v14
	v_cvt_pk_bf16_f32 v4, v94, v95
	v_add_f32_e32 v0, v97, v0
	v_cvt_pk_bf16_f32 v5, v96, v97
	v_add_f32_e32 v0, 0, v0
	s_add_i32 s8, s22, 1
	s_cmp_ge_u32 s8, s39
	s_cselect_b64 s[18:19], -1, 0
	s_and_b64 vcc, exec, s[18:19]
	v_lshl_add_u64 v[230:231], v[224:225], 0, s[16:17]
	s_cbranch_vccnz .LBB0_285
	s_add_i32 s8, s47, s43
	v_lshl_add_u64 v[14:15], v[230:231], 0, s[0:1]
	s_mov_b32 s9, m0
	s_mov_b32 m0, s8
	s_nop 0
	global_load_lds_dwordx4 v[14:15], off
	s_mov_b32 m0, s9

.LBB0_294:
	v_add_u32_e32 v241, s47, v251
	ds_read_b64_tr_b16 v[206:207], v241 offset:24576
	ds_read_b64_tr_b16 v[208:209], v241 offset:25088
	s_waitcnt lgkmcnt(9)
	v_mfma_f32_32x32x16_bf16 v[98:113], v[194:197], v[162:165], 0
	v_add_f32_e32 v2, v130, v131
	v_cvt_pk_bf16_f32 v150, v130, v131
	v_add_f32_e32 v2, v132, v2
	v_cvt_pk_bf16_f32 v151, v132, v133
	v_add_f32_e32 v2, v133, v2
	v_add_f32_e32 v2, v134, v2
	v_add_f32_e32 v2, v135, v2
	ds_read_b64_tr_b16 v[202:203], v241 offset:28672
	ds_read_b64_tr_b16 v[204:205], v241 offset:29184
	s_waitcnt lgkmcnt(10)
	v_mfma_f32_32x32x16_bf16 v[82:97], v[186:189], v[162:165], 0
	v_add_f32_e32 v2, v136, v2
	v_cvt_pk_bf16_f32 v152, v134, v135
	v_add_f32_e32 v2, v137, v2
	v_cvt_pk_bf16_f32 v153, v136, v137
	v_add_f32_e32 v2, v138, v2
	v_add_f32_e32 v2, v139, v2
	ds_read_b64_tr_b16 v[198:199], v241 offset:25600
	ds_read_b64_tr_b16 v[200:201], v241 offset:26112
	s_waitcnt lgkmcnt(11)
	v_mfma_f32_32x32x16_bf16 v[98:113], v[190:193], v[158:161], v[98:113]
	v_add_f32_e32 v2, v140, v2
	v_cvt_pk_bf16_f32 v10, v138, v139
	v_add_f32_e32 v2, v141, v2
	v_cvt_pk_bf16_f32 v11, v140, v141
	v_add_f32_e32 v2, v142, v2
	v_add_f32_e32 v2, v143, v2
	ds_read_b64_tr_b16 v[138:139], v241 offset:29696
	ds_read_b64_tr_b16 v[140:141], v241 offset:30208
	s_waitcnt lgkmcnt(12)
	v_mfma_f32_32x32x16_bf16 v[82:97], v[182:185], v[158:161], v[82:97]
	v_add_f32_e32 v2, v144, v2
	v_cvt_pk_bf16_f32 v12, v142, v143
	v_add_f32_e32 v2, v145, v2
	v_cvt_pk_bf16_f32 v13, v144, v145
	v_add_f32_e32 v2, v114, v2
	v_add_f32_e32 v2, v115, v2
	ds_read_b64_tr_b16 v[134:135], v241 offset:26624
	ds_read_b64_tr_b16 v[136:137], v241 offset:27136
	s_waitcnt lgkmcnt(13)
	v_mfma_f32_32x32x16_bf16 v[98:113], v[178:181], v[154:157], v[98:113]
	v_add_f32_e32 v2, v116, v2
	v_cvt_pk_bf16_f32 v6, v114, v115
	v_add_f32_e32 v2, v117, v2
	v_cvt_pk_bf16_f32 v7, v116, v117
	v_add_f32_e32 v2, v118, v2
	v_add_f32_e32 v2, v119, v2
	ds_read_b64_tr_b16 v[130:131], v241 offset:30720
	ds_read_b64_tr_b16 v[132:133], v241 offset:31232
	s_waitcnt lgkmcnt(14)
	v_mfma_f32_32x32x16_bf16 v[82:97], v[174:177], v[154:157], v[82:97]
	v_add_f32_e32 v2, v120, v2
	v_cvt_pk_bf16_f32 v8, v118, v119
	v_add_f32_e32 v2, v121, v2
	v_cvt_pk_bf16_f32 v9, v120, v121
	v_add_f32_e32 v2, v122, v2
	v_add_f32_e32 v2, v123, v2
	ds_read_b64_tr_b16 v[118:119], v241 offset:27648
	ds_read_b64_tr_b16 v[120:121], v241 offset:28160
	s_waitcnt lgkmcnt(14)
	v_mfma_f32_32x32x16_bf16 v[98:113], v[170:173], v[146:149], v[98:113]
	v_add_f32_e32 v2, v124, v2
	v_cvt_pk_bf16_f32 v3, v124, v125
	v_add_f32_e32 v2, v125, v2
	v_add_f32_e32 v2, v126, v2
	v_add_f32_e32 v142, v127, v2
	v_cvt_pk_bf16_f32 v2, v122, v123
	ds_read_b64_tr_b16 v[114:115], v241 offset:31744
	ds_read_b64_tr_b16 v[116:117], v241 offset:32256
	v_mfma_f32_32x32x16_bf16 v[82:97], v[166:169], v[146:149], v[82:97]
	v_add_f32_e32 v4, v128, v142
	v_cvt_pk_bf16_f32 v5, v128, v129
	v_add_f32_e32 v4, v129, v4
	v_add_f32_e32 v122, 0, v4
	v_cvt_pk_bf16_f32 v4, v126, v127
	s_add_i32 s13, s22, 2
	s_cmp_ge_u32 s13, s39
	s_cselect_b64 s[20:21], -1, 0
	s_and_b64 vcc, exec, s[20:21]
	s_cbranch_vccnz .LBB0_296
	s_add_i32 s8, s46, s43
	v_lshl_add_u64 v[124:125], v[230:231], 0, s[80:81]
	s_mov_b32 s9, m0
	s_mov_b32 m0, s8
	s_nop 0
	global_load_lds_dwordx4 v[124:125], off
	s_mov_b32 m0, s9

; __device__ __forceinline__ int crow(int r,int hi){return (r&3)+8*(r>>2)+4*hi;}
;     ...
;   {auto rr=__builtin_amdgcn_permlane32_swap(__float_as_uint(l_reg),__float_as_uint(l_reg),false,false);l_reg=__uint_as_float(rr[0])+__uint_as_float(rr[1]);}
;   if(hi==0)wsf[32+r32]=l_reg;asm volatile("s_waitcnt lgkmcnt(0)":::"memory");
;   float rli[16];
;   #pragma unroll
;   for(int r=0;r<16;++r)rli[r]=__builtin_amdgcn_rcpf(wsf[32+crow(r,hi)]);
;   if constexpr(DV2){ float*Orw=Oraw+(long)wid*QBLK*128;
;     #pragma unroll
;     for(int r=0;r<16;++r){const int orow=crow(r,hi);
;       #pragma unroll
;       for(int d0=0;d0<4;++d0) Orw[orow*128+d0*32+r32]=o[d0][r]*rli[r];}
;   } else {
;   bf16*Ow=OGu+(long)wid*QBLK*1024; const bf16*Zw=SZu+(long)wid*QBLK*1024;
;   { bf16*stg=(bf16*)(shm+LDS_OST)+wid*2048;
;     #pragma unroll
;     for(int r=0;r<16;++r){const int orow=crow(r,hi);
;       #pragma unroll
;       for(int d0=0;d0<2;++d0) stg[orow*64+d0*32+r32]=(bf16)(pk_bf16(o[d0][r]*rli[r],0.f)&0xffffu);}
;     asm volatile("s_waitcnt lgkmcnt(0)":::"memory");
;     #pragma unroll
;     for(int i=0;i<4;++i){const int row=i*8+(lane>>3),ch=lane&7; const u32x4 v=*(const u32x4*)(stg+row*64+ch*8); const u32x4 z=*(const u32x4*)(Zw+(long)row*1024+ch*8); u32x4 g;
;       #pragma unroll
;       for(int e=0;e<4;++e){ const float a0=__uint_as_float(v[e]<<16)*__uint_as_float(z[e]<<16), a1=__uint_as_float(v[e]&0xffff0000u)*__uint_as_float(z[e]&0xffff0000u); g[e]=pk_bf16(a0,a1); }
;       *(u32x4*)(Ow+(long)row*1024+ch*8)=g;} }
.LBB0_337:
	s_or_b64 exec, exec, s[6:7]
	s_waitcnt lgkmcnt(0)
	v_readlane_b32 s6, v255, 7
	ds_read_b128 v[2:5], v193 offset:49280
	ds_read_b128 v[6:9], v193 offset:49312
	s_lshl_b32 s6, s6, 7
	v_readlane_b32 s7, v254, 22
	s_add_u32 s10, s7, s6
	v_readlane_b32 s7, v254, 23
	s_addc_u32 s11, s7, 0
	v_readlane_b32 s7, v254, 24
	s_add_u32 s6, s7, s6
	v_readlane_b32 s7, v254, 41
	s_addc_u32 s7, s7, 0
	s_waitcnt lgkmcnt(1)
	v_rcp_f32_e32 v0, v2
	s_lshl_b64 s[8:9], s[4:5], 16
	s_add_u32 s6, s6, s8
	v_rcp_f32_e32 v10, v3
	s_addc_u32 s7, s7, s9
	s_lshl_b32 s4, s4, 12
	s_add_i32 s12, s4, 0
	v_lshlrev_b32_e32 v19, 9, v190
	v_lshlrev_b32_e32 v20, 1, v189
	v_add3_u32 v19, s12, v19, v20
	v_mul_f32_e32 v20, v34, v0
	v_mul_f32_e32 v0, v50, v0
	v_cvt_pk_bf16_f32 v0, v0, v1
	v_rcp_f32_e32 v11, v4
	ds_write_b16 v19, v0 offset:51264
	v_mul_f32_e32 v0, v35, v10
	v_cvt_pk_bf16_f32 v0, v0, v1
	ds_write_b16 v19, v0 offset:51328
	v_mul_f32_e32 v0, v51, v10
	v_cvt_pk_bf16_f32 v0, v0, v1
	v_rcp_f32_e32 v12, v5
	ds_write_b16 v19, v0 offset:51392
	v_mul_f32_e32 v0, v36, v11
	v_cvt_pk_bf16_f32 v0, v0, v1
	ds_write_b16 v19, v0 offset:51456
	v_mul_f32_e32 v0, v52, v11
	v_cvt_pk_bf16_f32 v0, v0, v1
	s_waitcnt lgkmcnt(4)
	v_rcp_f32_e32 v13, v6
	ds_write_b16 v19, v0 offset:51520
	v_mul_f32_e32 v0, v37, v12
	v_cvt_pk_bf16_f32 v0, v0, v1
	ds_write_b16 v19, v0 offset:51584
	v_mul_f32_e32 v0, v53, v12
	v_cvt_pk_bf16_f32 v0, v0, v1
	v_rcp_f32_e32 v14, v7
	ds_write_b16 v19, v0 offset:51648
	v_mul_f32_e32 v0, v38, v13
	v_cvt_pk_bf16_f32 v0, v0, v1
	ds_write_b16 v19, v0 offset:52224
	v_mul_f32_e32 v0, v54, v13
	v_cvt_pk_bf16_f32 v0, v0, v1
	v_rcp_f32_e32 v15, v8
	ds_write_b16 v19, v0 offset:52288
	v_mul_f32_e32 v0, v39, v14
	v_cvt_pk_bf16_f32 v0, v0, v1
	ds_write_b16 v19, v0 offset:52352
	v_mul_f32_e32 v0, v55, v14
	ds_read_b128 v[2:5], v193 offset:49344
	v_cvt_pk_bf16_f32 v0, v0, v1
	v_rcp_f32_e32 v18, v9
	ds_write_b16 v19, v0 offset:52416
	v_mul_f32_e32 v0, v40, v15
	v_cvt_pk_bf16_f32 v0, v0, v1
	ds_write_b16 v19, v0 offset:52480
	v_mul_f32_e32 v0, v56, v15
	v_cvt_pk_bf16_f32 v0, v0, v1
	ds_read_b128 v[6:9], v193 offset:49376
	s_waitcnt lgkmcnt(3)
	v_rcp_f32_e32 v2, v2
	ds_write_b16 v19, v0 offset:52544
	v_mul_f32_e32 v0, v41, v18
	v_cvt_pk_bf16_f32 v0, v0, v1
	ds_write_b16 v19, v0 offset:52608
	v_mul_f32_e32 v0, v57, v18
	v_cvt_pk_bf16_f32 v0, v0, v1
	v_rcp_f32_e32 v3, v3
	ds_write_b16 v19, v0 offset:52672
	v_mul_f32_e32 v0, v42, v2
	v_cvt_pk_bf16_f32 v0, v0, v1
	ds_write_b16 v19, v0 offset:53248
	v_mul_f32_e32 v0, v58, v2
	v_cvt_pk_bf16_f32 v0, v0, v1
	v_rcp_f32_e32 v4, v4
	ds_write_b16 v19, v0 offset:53312
	v_mul_f32_e32 v0, v43, v3
	v_cvt_pk_bf16_f32 v0, v0, v1
	ds_write_b16 v19, v0 offset:53376
	v_mul_f32_e32 v0, v59, v3
	v_cvt_pk_bf16_f32 v0, v0, v1
	v_rcp_f32_e32 v5, v5
	ds_write_b16 v19, v0 offset:53440
	v_mul_f32_e32 v0, v44, v4
	v_cvt_pk_bf16_f32 v0, v0, v1
	ds_write_b16 v19, v0 offset:53504
	v_mul_f32_e32 v0, v60, v4
	v_cvt_pk_bf16_f32 v0, v0, v1
	s_waitcnt lgkmcnt(8)
	v_rcp_f32_e32 v6, v6
	ds_write_b16 v19, v0 offset:53568
	v_mul_f32_e32 v0, v45, v5
	v_cvt_pk_bf16_f32 v0, v0, v1
	ds_write_b16 v19, v0 offset:53632
	v_mul_f32_e32 v0, v61, v5
	v_cvt_pk_bf16_f32 v0, v0, v1
	v_rcp_f32_e32 v7, v7
	ds_write_b16 v19, v0 offset:53696
	v_mul_f32_e32 v0, v46, v6
	v_cvt_pk_bf16_f32 v0, v0, v1
	ds_write_b16 v19, v0 offset:54272
	v_mul_f32_e32 v0, v62, v6
	v_cvt_pk_bf16_f32 v0, v0, v1
	v_rcp_f32_e32 v8, v8
	ds_write_b16 v19, v0 offset:54336
	v_mul_f32_e32 v0, v47, v7
	v_cvt_pk_bf16_f32 v0, v0, v1
	ds_write_b16 v19, v0 offset:54400
	v_mul_f32_e32 v0, v63, v7
	v_cvt_pk_bf16_f32 v0, v0, v1
	v_rcp_f32_e32 v9, v9
	ds_write_b16 v19, v0 offset:54464
	v_mul_f32_e32 v0, v48, v8
	v_cvt_pk_bf16_f32 v0, v0, v1
	ds_write_b16 v19, v0 offset:54528
	v_mul_f32_e32 v0, v64, v8
	v_cvt_pk_bf16_f32 v0, v0, v1
	ds_write_b16 v19, v0 offset:54592
	v_mul_f32_e32 v0, v49, v9
	v_cvt_pk_bf16_f32 v0, v0, v1
	ds_write_b16 v19, v0 offset:54656
	v_mul_f32_e32 v0, v65, v9
	v_cvt_pk_bf16_f32 v0, v0, v1
	ds_write_b16 v19, v0 offset:54720
	s_add_u32 s4, s10, s8
	v_lshlrev_b32_e32 v0, 1, v188
	s_addc_u32 s5, s11, s9
	v_lshrrev_b32_e32 v14, 3, v17
	v_and_b32_e32 v0, 0x70, v0
	v_cvt_pk_bf16_f32 v20, v20, v1
	ds_write_b16 v19, v20 offset:51200
	v_add_u32_e32 v17, s12, v0
	v_lshl_add_u64 v[10:11], s[4:5], 0, v[0:1]
	v_lshl_add_u64 v[12:13], s[6:7], 0, v[0:1]
	v_mov_b32_e32 v117, 0
	v_lshlrev_b32_e32 v116, 11, v14
	v_lshl_add_u64 v[118:119], v[10:11], 0, v[116:117]
	global_load_dwordx4 v[100:103], v[118:119], off
	v_or_b32_e32 v116, 8, v14
	v_lshlrev_b32_e32 v116, 11, v116
	v_lshl_add_u64 v[118:119], v[10:11], 0, v[116:117]
	global_load_dwordx4 v[104:107], v[118:119], off
	v_or_b32_e32 v116, 16, v14
	v_lshlrev_b32_e32 v116, 11, v116
	v_lshl_add_u64 v[118:119], v[10:11], 0, v[116:117]
	global_load_dwordx4 v[108:111], v[118:119], off
	v_or_b32_e32 v116, 24, v14
	v_lshlrev_b32_e32 v116, 11, v116
	v_lshl_add_u64 v[118:119], v[10:11], 0, v[116:117]
	global_load_dwordx4 v[112:115], v[118:119], off
	v_lshlrev_b32_e32 v0, 11, v14
	s_waitcnt lgkmcnt(0)
;     ...
;     for(int i=0;i<4;++i){const int row=i*8+(lane>>3),ch=lane&7; const u32x4 v=*(const u32x4*)(stg+row*64+ch*8); const u32x4 z=*(const u32x4*)(Zw+(long)row*1024+ch*8); u32x4 g;
;       #pragma unroll
;       for(int e=0;e<4;++e){ const float a0=__uint_as_float(v[e]<<16)*__uint_as_float(z[e]<<16), a1=__uint_as_float(v[e]&0xffff0000u)*__uint_as_float(z[e]&0xffff0000u); g[e]=pk_bf16(a0,a1); }
;       *(u32x4*)(Ow+(long)row*1024+ch*8)=g;} }
	v_lshl_add_u64 v[2:3], v[10:11], 0, v[0:1]
	v_lshl_add_u32 v6, v14, 7, v17
	ds_read_b128 v[6:9], v6 offset:51200
	s_waitcnt lgkmcnt(0)
	v_lshlrev_b32_e32 v15, 16, v6
	v_and_b32_e32 v6, 0xffff0000, v6
	s_waitcnt vmcnt(3)
	v_lshlrev_b32_e32 v18, 16, v100
	v_and_b32_e32 v2, 0xffff0000, v100
	v_mul_f32_e32 v15, v18, v15
	v_mul_f32_e32 v2, v2, v6
	v_cvt_pk_bf16_f32 v2, v15, v2
	v_lshlrev_b32_e32 v6, 16, v7
	v_lshlrev_b32_e32 v15, 16, v101
	v_and_b32_e32 v3, 0xffff0000, v101
	v_and_b32_e32 v7, 0xffff0000, v7
	v_mul_f32_e32 v6, v15, v6
	v_mul_f32_e32 v3, v3, v7
	v_cvt_pk_bf16_f32 v3, v6, v3
	v_lshlrev_b32_e32 v6, 16, v8
	v_lshlrev_b32_e32 v7, 16, v102
	v_mul_f32_e32 v6, v7, v6
	v_and_b32_e32 v4, 0xffff0000, v102
	v_and_b32_e32 v7, 0xffff0000, v8
	v_mul_f32_e32 v4, v4, v7
	v_cvt_pk_bf16_f32 v4, v6, v4
	v_lshlrev_b32_e32 v6, 16, v9
	v_lshlrev_b32_e32 v7, 16, v103
	v_mul_f32_e32 v6, v7, v6
	v_and_b32_e32 v5, 0xffff0000, v103
	v_and_b32_e32 v7, 0xffff0000, v9
	v_mul_f32_e32 v5, v5, v7
	v_cvt_pk_bf16_f32 v5, v6, v5
	v_lshl_add_u64 v[6:7], v[12:13], 0, v[0:1]
	global_store_dwordx4 v[6:7], v[2:5], off
	v_or_b32_e32 v6, 8, v14
	v_lshlrev_b32_e32 v0, 11, v6
	v_lshl_add_u64 v[2:3], v[10:11], 0, v[0:1]
	v_lshl_add_u32 v6, v6, 7, v17
	ds_read_b128 v[6:9], v6 offset:51200
	s_waitcnt lgkmcnt(0)
	v_lshlrev_b32_e32 v15, 16, v6
	v_and_b32_e32 v6, 0xffff0000, v6
	s_waitcnt vmcnt(3)
	v_lshlrev_b32_e32 v18, 16, v104
	v_and_b32_e32 v2, 0xffff0000, v104
	v_mul_f32_e32 v15, v18, v15
	v_mul_f32_e32 v2, v2, v6
	v_cvt_pk_bf16_f32 v2, v15, v2
	v_lshlrev_b32_e32 v6, 16, v7
	v_lshlrev_b32_e32 v15, 16, v105
	v_and_b32_e32 v3, 0xffff0000, v105
	v_and_b32_e32 v7, 0xffff0000, v7
	v_mul_f32_e32 v6, v15, v6
	v_mul_f32_e32 v3, v3, v7
	v_cvt_pk_bf16_f32 v3, v6, v3
	v_lshlrev_b32_e32 v6, 16, v8
	v_lshlrev_b32_e32 v7, 16, v106
	v_mul_f32_e32 v6, v7, v6
	v_and_b32_e32 v4, 0xffff0000, v106
	v_and_b32_e32 v7, 0xffff0000, v8
	v_mul_f32_e32 v4, v4, v7
	v_cvt_pk_bf16_f32 v4, v6, v4
	v_lshlrev_b32_e32 v6, 16, v9
	v_lshlrev_b32_e32 v7, 16, v107
	v_mul_f32_e32 v6, v7, v6
	v_and_b32_e32 v5, 0xffff0000, v107
	v_and_b32_e32 v7, 0xffff0000, v9
	v_mul_f32_e32 v5, v5, v7
	v_cvt_pk_bf16_f32 v5, v6, v5
	v_lshl_add_u64 v[6:7], v[12:13], 0, v[0:1]
	global_store_dwordx4 v[6:7], v[2:5], off
	v_or_b32_e32 v6, 16, v14
	v_lshlrev_b32_e32 v0, 11, v6
	v_lshl_add_u64 v[2:3], v[10:11], 0, v[0:1]
	v_lshl_add_u32 v6, v6, 7, v17
	ds_read_b128 v[6:9], v6 offset:51200
	v_or_b32_e32 v18, 24, v14
	v_lshl_add_u64 v[14:15], v[12:13], 0, v[0:1]
	v_lshlrev_b32_e32 v0, 11, v18
	v_lshl_add_u64 v[10:11], v[10:11], 0, v[0:1]
	s_waitcnt lgkmcnt(0)
	v_lshlrev_b32_e32 v19, 16, v6
	v_and_b32_e32 v6, 0xffff0000, v6
	v_lshlrev_b32_e32 v20, 16, v7
	v_and_b32_e32 v7, 0xffff0000, v7
	v_lshlrev_b32_e32 v21, 16, v8
	v_and_b32_e32 v8, 0xffff0000, v8
	v_lshlrev_b32_e32 v22, 16, v9
	v_and_b32_e32 v9, 0xffff0000, v9
	s_waitcnt vmcnt(3)
	v_lshlrev_b32_e32 v23, 16, v108
	v_and_b32_e32 v2, 0xffff0000, v108
	v_lshlrev_b32_e32 v24, 16, v109
	v_and_b32_e32 v3, 0xffff0000, v109
	v_lshlrev_b32_e32 v25, 16, v110
	v_and_b32_e32 v4, 0xffff0000, v110
	v_lshlrev_b32_e32 v26, 16, v111
	v_and_b32_e32 v5, 0xffff0000, v111
	v_mul_f32_e32 v2, v2, v6
	v_mul_f32_e32 v3, v3, v7
	v_mul_f32_e32 v4, v4, v8
	v_mul_f32_e32 v5, v5, v9
	v_mul_f32_e32 v19, v23, v19
	v_mul_f32_e32 v6, v24, v20
	v_mul_f32_e32 v7, v25, v21
	v_mul_f32_e32 v8, v26, v22
	v_cvt_pk_bf16_f32 v2, v19, v2
	v_cvt_pk_bf16_f32 v3, v6, v3
	v_cvt_pk_bf16_f32 v4, v7, v4
	v_cvt_pk_bf16_f32 v5, v8, v5
	global_store_dwordx4 v[14:15], v[2:5], off
	v_lshl_add_u32 v6, v18, 7, v17
	ds_read_b128 v[6:9], v6 offset:51200
	s_waitcnt lgkmcnt(0)
	v_lshlrev_b32_e32 v10, 16, v6
	v_and_b32_e32 v6, 0xffff0000, v6
	v_lshlrev_b32_e32 v11, 16, v7
	v_and_b32_e32 v7, 0xffff0000, v7
	v_lshlrev_b32_e32 v14, 16, v8
	v_and_b32_e32 v8, 0xffff0000, v8
	v_lshlrev_b32_e32 v15, 16, v9
	v_and_b32_e32 v9, 0xffff0000, v9
	s_waitcnt vmcnt(3)
	v_lshlrev_b32_e32 v17, 16, v112
	v_and_b32_e32 v2, 0xffff0000, v112
	v_lshlrev_b32_e32 v18, 16, v113
	v_and_b32_e32 v3, 0xffff0000, v113
	v_lshlrev_b32_e32 v19, 16, v114
	v_and_b32_e32 v4, 0xffff0000, v114
	v_lshlrev_b32_e32 v20, 16, v115
	v_and_b32_e32 v5, 0xffff0000, v115
	v_mul_f32_e32 v2, v2, v6
	v_mul_f32_e32 v6, v18, v11
	v_mul_f32_e32 v3, v3, v7
	v_mul_f32_e32 v7, v19, v14
	v_mul_f32_e32 v4, v4, v8
	v_mul_f32_e32 v5, v5, v9
	v_cvt_pk_bf16_f32 v3, v6, v3
	v_cvt_pk_bf16_f32 v4, v7, v4
	v_lshl_add_u64 v[6:7], v[12:13], 0, v[0:1]
	v_mul_f32_e32 v10, v17, v10
	v_mul_f32_e32 v8, v20, v15
	v_cvt_pk_bf16_f32 v2, v10, v2
	v_cvt_pk_bf16_f32 v5, v8, v5
	global_store_dwordx4 v[6:7], v[2:5], off
	s_waitcnt lgkmcnt(0)
	s_barrier

.LBB0_351:
	s_add_i32 s92, s9, -2
	v_add_u32_e32 v17, s4, v216
	ds_read_b64_tr_b16 v[184:185], v17 offset:24576
	ds_read_b64_tr_b16 v[186:187], v17 offset:25088
	s_waitcnt lgkmcnt(9)
	v_mfma_f32_32x32x16_bf16 v[128:143], v[180:183], v[176:179], v[64:79]
	v_add_f32_e32 v2, v96, v97
	v_cvt_pk_bf16_f32 v160, v96, v97
	v_add_f32_e32 v2, v98, v2
	v_cvt_pk_bf16_f32 v161, v98, v99
	v_add_f32_e32 v2, v99, v2
	v_add_f32_e32 v2, v100, v2
	v_add_f32_e32 v2, v101, v2
	ds_read_b64_tr_b16 v[180:181], v17 offset:28672
	ds_read_b64_tr_b16 v[182:183], v17 offset:29184
	s_waitcnt lgkmcnt(10)
	v_mfma_f32_32x32x16_bf16 v[112:127], v[156:159], v[176:179], v[64:79]
	v_add_f32_e32 v2, v102, v2
	v_cvt_pk_bf16_f32 v162, v100, v101
	v_add_f32_e32 v2, v103, v2
	v_cvt_pk_bf16_f32 v163, v102, v103
	v_add_f32_e32 v2, v104, v2
	v_add_f32_e32 v2, v105, v2
	ds_read_b64_tr_b16 v[96:97], v17 offset:25600
	ds_read_b64_tr_b16 v[98:99], v17 offset:26112
	s_waitcnt lgkmcnt(11)
	v_mfma_f32_32x32x16_bf16 v[128:143], v[152:155], v[172:175], v[128:143]
	v_add_f32_e32 v2, v106, v2
	v_cvt_pk_bf16_f32 v10, v104, v105
	v_add_f32_e32 v2, v107, v2
	v_cvt_pk_bf16_f32 v11, v106, v107
	v_add_f32_e32 v2, v108, v2
	v_add_f32_e32 v2, v109, v2
	ds_read_b64_tr_b16 v[100:101], v17 offset:29696
	ds_read_b64_tr_b16 v[102:103], v17 offset:30208
	s_waitcnt lgkmcnt(12)
	v_mfma_f32_32x32x16_bf16 v[112:127], v[148:151], v[172:175], v[112:127]
	v_add_f32_e32 v2, v110, v2
	v_cvt_pk_bf16_f32 v12, v108, v109
	v_add_f32_e32 v2, v111, v2
	v_cvt_pk_bf16_f32 v13, v110, v111
	v_add_f32_e32 v2, v80, v2
	v_add_f32_e32 v2, v81, v2
	ds_read_b64_tr_b16 v[104:105], v17 offset:26624
	ds_read_b64_tr_b16 v[106:107], v17 offset:27136
	s_waitcnt lgkmcnt(13)
	v_mfma_f32_32x32x16_bf16 v[128:143], v[144:147], v[168:171], v[128:143]
	v_add_f32_e32 v2, v82, v2
	v_cvt_pk_bf16_f32 v6, v80, v81
	v_add_f32_e32 v2, v83, v2
	v_cvt_pk_bf16_f32 v7, v82, v83
	v_add_f32_e32 v2, v84, v2
	v_add_f32_e32 v2, v85, v2
	ds_read_b64_tr_b16 v[80:81], v17 offset:30720
	ds_read_b64_tr_b16 v[82:83], v17 offset:31232
	s_waitcnt lgkmcnt(14)
	v_mfma_f32_32x32x16_bf16 v[112:127], v[26:29], v[168:171], v[112:127]
	v_add_f32_e32 v2, v86, v2
	v_cvt_pk_bf16_f32 v8, v84, v85
	v_add_f32_e32 v2, v87, v2
	v_cvt_pk_bf16_f32 v9, v86, v87
	v_add_f32_e32 v2, v88, v2
	v_add_f32_e32 v2, v89, v2
	ds_read_b64_tr_b16 v[84:85], v17 offset:27648
	ds_read_b64_tr_b16 v[86:87], v17 offset:28160
	s_waitcnt lgkmcnt(14)
	v_mfma_f32_32x32x16_bf16 v[128:143], v[22:25], v[164:167], v[128:143]
	v_add_f32_e32 v2, v90, v2
	v_cvt_pk_bf16_f32 v3, v90, v91
	v_add_f32_e32 v2, v91, v2
	v_add_f32_e32 v2, v92, v2
	v_add_f32_e32 v22, v93, v2
	v_cvt_pk_bf16_f32 v2, v88, v89
	ds_read_b64_tr_b16 v[88:89], v17 offset:31744
	ds_read_b64_tr_b16 v[90:91], v17 offset:32256
	v_mfma_f32_32x32x16_bf16 v[112:127], v[18:21], v[164:167], v[112:127]
	v_add_f32_e32 v4, v94, v22
	v_cvt_pk_bf16_f32 v5, v94, v95
	v_add_f32_e32 v4, v95, v4
	v_add_f32_e32 v108, 0, v4
	v_cvt_pk_bf16_f32 v4, v92, v93
	s_add_i32 s6, s9, -1
	s_add_i32 s4, s93, s33
	s_add_i32 s7, s6, s8
	s_cmp_gt_u32 s92, 2
	s_cselect_b64 s[10:11], -1, 0
	s_mov_b32 s5, m0
	s_mov_b32 m0, s4
	s_nop 0
	global_load_lds_dwordx4 v[190:191], off
	s_mov_b32 m0, s5
	s_and_b64 s[4:5], s[10:11], exec
	s_cselect_b32 s82, s7, s6
	s_lshl_b64 s[4:5], s[82:83], 13
	v_lshl_add_u64 v[18:19], v[14:15], 0, s[4:5]
	s_add_i32 s4, s91, s88
	s_mov_b32 s5, m0
	s_mov_b32 m0, s4
	s_nop 0
	global_load_lds_dwordx4 v[18:19], off
	s_mov_b32 m0, s5
	s_cmp_lt_u32 s92, 4
	s_cbranch_scc1 .LBB0_419
	s_add_i32 s4, s90, s9
	s_add_i32 s4, s4, -6
	s_cmp_gt_u32 s4, 7
	s_cbranch_scc1 .LBB0_418
	v_mov_b32_e32 v17, 0
	v_mov_b32_e32 v18, 0
	s_and_saveexec_b64 s[4:5], s[12:13]
	ds_read_b32 v18, v193
	s_or_b64 exec, exec, s[4:5]
	s_and_saveexec_b64 s[4:5], s[14:15]
	ds_read_b32 v17, v193 offset:128
	s_or_b64 exec, exec, s[4:5]
	v_mov_b32_e32 v19, 0
	v_mov_b32_e32 v20, 0
	s_and_saveexec_b64 s[4:5], s[16:17]
	ds_read_b32 v20, v193 offset:4
	s_or_b64 exec, exec, s[4:5]
	s_and_saveexec_b64 s[4:5], s[18:19]
	ds_read_b32 v19, v193 offset:132
	s_or_b64 exec, exec, s[4:5]
	v_mov_b32_e32 v21, 0
	v_mov_b32_e32 v22, 0
	s_and_saveexec_b64 s[4:5], s[20:21]
	ds_read_b32 v22, v193 offset:8
	s_or_b64 exec, exec, s[4:5]
	s_and_saveexec_b64 s[4:5], s[22:23]
	ds_read_b32 v21, v193 offset:136
	s_or_b64 exec, exec, s[4:5]
	v_mov_b32_e32 v23, 0
	v_mov_b32_e32 v24, 0
	s_and_saveexec_b64 s[4:5], s[24:25]
	ds_read_b32 v24, v193 offset:12
	s_or_b64 exec, exec, s[4:5]
	s_and_saveexec_b64 s[4:5], s[26:27]
	ds_read_b32 v23, v193 offset:140
	s_or_b64 exec, exec, s[4:5]
	v_mov_b32_e32 v25, 0
	v_mov_b32_e32 v26, 0
	s_and_saveexec_b64 s[4:5], s[28:29]
	ds_read_b32 v26, v193 offset:32
	s_or_b64 exec, exec, s[4:5]
	s_and_saveexec_b64 s[4:5], s[30:31]
	ds_read_b32 v25, v193 offset:160
	s_or_b64 exec, exec, s[4:5]
	v_mov_b32_e32 v27, 0
	v_mov_b32_e32 v28, 0
	s_and_saveexec_b64 s[4:5], s[34:35]
	ds_read_b32 v28, v193 offset:36
	s_or_b64 exec, exec, s[4:5]
	s_and_saveexec_b64 s[4:5], s[36:37]
	ds_read_b32 v27, v193 offset:164
	s_or_b64 exec, exec, s[4:5]
	v_mov_b32_e32 v29, 0
	v_mov_b32_e32 v30, 0
	s_and_saveexec_b64 s[4:5], s[38:39]
	ds_read_b32 v30, v193 offset:40
	s_or_b64 exec, exec, s[4:5]
	s_and_saveexec_b64 s[4:5], s[40:41]
	ds_read_b32 v29, v193 offset:168
	s_or_b64 exec, exec, s[4:5]
	v_mov_b32_e32 v31, 0
	v_mov_b32_e32 v92, 0
	s_and_saveexec_b64 s[4:5], s[42:43]
	ds_read_b32 v92, v193 offset:44
	s_or_b64 exec, exec, s[4:5]
	s_and_saveexec_b64 s[4:5], s[44:45]
	ds_read_b32 v31, v193 offset:172
	s_or_b64 exec, exec, s[4:5]
	v_mov_b32_e32 v93, 0
	v_mov_b32_e32 v94, 0
	s_and_saveexec_b64 s[4:5], s[46:47]
	ds_read_b32 v94, v193 offset:64
	s_or_b64 exec, exec, s[4:5]
	s_and_saveexec_b64 s[4:5], s[48:49]
	ds_read_b32 v93, v193 offset:192
	s_or_b64 exec, exec, s[4:5]
	v_mov_b32_e32 v95, 0
	v_mov_b32_e32 v109, 0
	s_and_saveexec_b64 s[4:5], s[50:51]
	ds_read_b32 v109, v193 offset:68
	s_or_b64 exec, exec, s[4:5]
	s_and_saveexec_b64 s[4:5], s[52:53]
	ds_read_b32 v95, v193 offset:196
	s_or_b64 exec, exec, s[4:5]
	v_mov_b32_e32 v110, 0
	v_mov_b32_e32 v111, 0
	s_and_saveexec_b64 s[4:5], s[54:55]
	ds_read_b32 v111, v193 offset:72
	s_or_b64 exec, exec, s[4:5]
	s_and_saveexec_b64 s[4:5], s[56:57]
	ds_read_b32 v110, v193 offset:200
	s_or_b64 exec, exec, s[4:5]
	v_mov_b32_e32 v144, 0
	v_mov_b32_e32 v145, 0
	s_and_saveexec_b64 s[4:5], s[58:59]
	ds_read_b32 v145, v193 offset:76
	s_or_b64 exec, exec, s[4:5]
	s_and_saveexec_b64 s[4:5], s[60:61]
	ds_read_b32 v144, v193 offset:204
	s_or_b64 exec, exec, s[4:5]
	v_mov_b32_e32 v146, 0
	v_mov_b32_e32 v147, 0
	s_and_saveexec_b64 s[4:5], s[62:63]
	ds_read_b32 v147, v193 offset:96
	s_or_b64 exec, exec, s[4:5]
	s_and_saveexec_b64 s[4:5], s[64:65]
	ds_read_b32 v146, v193 offset:224
	s_or_b64 exec, exec, s[4:5]
	v_mov_b32_e32 v148, 0
	v_mov_b32_e32 v149, 0
	s_and_saveexec_b64 s[4:5], s[66:67]
	ds_read_b32 v149, v193 offset:100
	s_or_b64 exec, exec, s[4:5]
	s_and_saveexec_b64 s[4:5], s[68:69]
	ds_read_b32 v148, v193 offset:228
	s_or_b64 exec, exec, s[4:5]
	v_mov_b32_e32 v150, 0
	v_mov_b32_e32 v151, 0
	s_and_saveexec_b64 s[4:5], s[70:71]
	ds_read_b32 v151, v193 offset:104
	s_or_b64 exec, exec, s[4:5]
	s_and_saveexec_b64 s[4:5], s[72:73]
	ds_read_b32 v150, v193 offset:232
	s_or_b64 exec, exec, s[4:5]
	v_mov_b32_e32 v152, 0
	v_mov_b32_e32 v153, 0
	s_and_saveexec_b64 s[4:5], s[74:75]
	ds_read_b32 v153, v193 offset:108
	s_or_b64 exec, exec, s[4:5]
	s_and_saveexec_b64 s[4:5], s[76:77]
	ds_read_b32 v152, v193 offset:236
	s_or_b64 exec, exec, s[4:5]
	s_waitcnt lgkmcnt(0)
	v_add_f32_e32 v17, v112, v17
	v_cndmask_b32_e64 v112, v16, v17, s[14:15]
	v_add_f32_e32 v17, v129, v20
	v_cndmask_b32_e64 v129, v16, v17, s[16:17]
	v_add_f32_e32 v17, v113, v19
	v_cndmask_b32_e64 v113, v16, v17, s[18:19]
	v_add_f32_e32 v17, v130, v22
	v_cndmask_b32_e64 v130, v16, v17, s[20:21]
	v_add_f32_e32 v17, v114, v21
	v_cndmask_b32_e64 v114, v16, v17, s[22:23]
	v_add_f32_e32 v17, v131, v24
	v_cndmask_b32_e64 v131, v16, v17, s[24:25]
	v_add_f32_e32 v17, v115, v23
	v_cndmask_b32_e64 v115, v16, v17, s[26:27]
	v_add_f32_e32 v17, v132, v26
	v_cndmask_b32_e64 v132, v16, v17, s[28:29]
	v_add_f32_e32 v17, v116, v25
	v_cndmask_b32_e64 v116, v16, v17, s[30:31]
	v_add_f32_e32 v17, v133, v28
	v_cndmask_b32_e64 v133, v16, v17, s[34:35]
	v_add_f32_e32 v17, v117, v27
	v_cndmask_b32_e64 v117, v16, v17, s[36:37]
	v_add_f32_e32 v17, v134, v30
	v_cndmask_b32_e64 v134, v16, v17, s[38:39]
	v_add_f32_e32 v17, v118, v29
	v_cndmask_b32_e64 v118, v16, v17, s[40:41]
	v_add_f32_e32 v17, v135, v92
	v_cndmask_b32_e64 v135, v16, v17, s[42:43]
	v_add_f32_e32 v17, v119, v31
	v_cndmask_b32_e64 v119, v16, v17, s[44:45]
	v_add_f32_e32 v17, v136, v94
	v_cndmask_b32_e64 v136, v16, v17, s[46:47]
	v_add_f32_e32 v17, v120, v93
	v_cndmask_b32_e64 v120, v16, v17, s[48:49]
	v_add_f32_e32 v17, v137, v109
	v_cndmask_b32_e64 v137, v16, v17, s[50:51]
	v_add_f32_e32 v17, v121, v95
	v_cndmask_b32_e64 v121, v16, v17, s[52:53]
	v_add_f32_e32 v17, v138, v111
	v_cndmask_b32_e64 v138, v16, v17, s[54:55]
	v_add_f32_e32 v17, v122, v110
	v_cndmask_b32_e64 v122, v16, v17, s[56:57]
	v_add_f32_e32 v17, v139, v145
	v_cndmask_b32_e64 v139, v16, v17, s[58:59]
	v_add_f32_e32 v17, v123, v144
	v_cndmask_b32_e64 v123, v16, v17, s[60:61]
	v_add_f32_e32 v17, v140, v147
	v_cndmask_b32_e64 v140, v16, v17, s[62:63]
	v_add_f32_e32 v17, v124, v146
	v_cndmask_b32_e64 v124, v16, v17, s[64:65]
	v_add_f32_e32 v17, v141, v149
	v_cndmask_b32_e64 v141, v16, v17, s[66:67]
	v_add_f32_e32 v17, v125, v148
	v_cndmask_b32_e64 v125, v16, v17, s[68:69]
	v_add_f32_e32 v17, v142, v151
	v_cndmask_b32_e64 v142, v16, v17, s[70:71]
	v_add_f32_e32 v17, v126, v150
	v_cndmask_b32_e64 v126, v16, v17, s[72:73]
	v_add_f32_e32 v17, v143, v153
	v_add_f32_e32 v18, v128, v18
	v_cndmask_b32_e64 v143, v16, v17, s[74:75]
	v_add_f32_e32 v17, v127, v152
	v_cndmask_b32_e64 v128, v16, v18, s[12:13]
	v_cndmask_b32_e64 v127, v16, v17, s[76:77]
	s_branch .LBB0_419

.LBB0_422:
	s_add_i32 s4, s91, 0x2000
	s_cmpk_lg_i32 s91, 0x4000
	s_cselect_b32 s94, s4, 0
	v_add_u32_e32 v17, s93, v216
	ds_read_b64_tr_b16 v[148:149], v17 offset:24576
	ds_read_b64_tr_b16 v[150:151], v17 offset:25088
	s_waitcnt lgkmcnt(9)
	v_mfma_f32_32x32x16_bf16 v[96:111], v[92:95], v[176:179], v[64:79]
	v_add_f32_e32 v2, v128, v129
	v_cvt_pk_bf16_f32 v160, v128, v129
	v_add_f32_e32 v2, v130, v2
	v_cvt_pk_bf16_f32 v161, v130, v131
	v_add_f32_e32 v2, v131, v2
	v_add_f32_e32 v2, v132, v2
	v_add_f32_e32 v2, v133, v2
	ds_read_b64_tr_b16 v[144:145], v17 offset:28672
	ds_read_b64_tr_b16 v[146:147], v17 offset:29184
	s_waitcnt lgkmcnt(10)
	v_mfma_f32_32x32x16_bf16 v[80:95], v[180:183], v[176:179], v[64:79]
	v_add_f32_e32 v2, v134, v2
	v_cvt_pk_bf16_f32 v162, v132, v133
	v_add_f32_e32 v2, v135, v2
	v_cvt_pk_bf16_f32 v163, v134, v135
	v_add_f32_e32 v2, v136, v2
	v_add_f32_e32 v2, v137, v2
	ds_read_b64_tr_b16 v[128:129], v17 offset:25600
	ds_read_b64_tr_b16 v[130:131], v17 offset:26112
	s_waitcnt lgkmcnt(11)
	v_mfma_f32_32x32x16_bf16 v[96:111], v[184:187], v[172:175], v[96:111]
	v_add_f32_e32 v2, v138, v2
	v_cvt_pk_bf16_f32 v10, v136, v137
	v_add_f32_e32 v2, v139, v2
	v_cvt_pk_bf16_f32 v11, v138, v139
	v_add_f32_e32 v2, v140, v2
	v_add_f32_e32 v2, v141, v2
	ds_read_b64_tr_b16 v[132:133], v17 offset:29696
	ds_read_b64_tr_b16 v[134:135], v17 offset:30208
	s_waitcnt lgkmcnt(12)
	v_mfma_f32_32x32x16_bf16 v[80:95], v[156:159], v[172:175], v[80:95]
	v_add_f32_e32 v2, v142, v2
	v_cvt_pk_bf16_f32 v12, v140, v141
	v_add_f32_e32 v2, v143, v2
	v_cvt_pk_bf16_f32 v13, v142, v143
	v_add_f32_e32 v2, v112, v2
	v_add_f32_e32 v2, v113, v2
	ds_read_b64_tr_b16 v[136:137], v17 offset:26624
	ds_read_b64_tr_b16 v[138:139], v17 offset:27136
	s_waitcnt lgkmcnt(13)
	v_mfma_f32_32x32x16_bf16 v[96:111], v[152:155], v[168:171], v[96:111]
	v_add_f32_e32 v2, v114, v2
	v_cvt_pk_bf16_f32 v6, v112, v113
	v_add_f32_e32 v2, v115, v2
	v_cvt_pk_bf16_f32 v7, v114, v115
	v_add_f32_e32 v2, v116, v2
	v_add_f32_e32 v2, v117, v2
	ds_read_b64_tr_b16 v[112:113], v17 offset:30720
	ds_read_b64_tr_b16 v[114:115], v17 offset:31232
	s_waitcnt lgkmcnt(14)
	v_mfma_f32_32x32x16_bf16 v[80:95], v[26:29], v[168:171], v[80:95]
	v_add_f32_e32 v2, v118, v2
	v_cvt_pk_bf16_f32 v8, v116, v117
	v_add_f32_e32 v2, v119, v2
	v_cvt_pk_bf16_f32 v9, v118, v119
	v_add_f32_e32 v2, v120, v2
	v_add_f32_e32 v2, v121, v2
	ds_read_b64_tr_b16 v[116:117], v17 offset:27648
	ds_read_b64_tr_b16 v[118:119], v17 offset:28160
	s_waitcnt lgkmcnt(14)
	v_mfma_f32_32x32x16_bf16 v[96:111], v[22:25], v[164:167], v[96:111]
	v_add_f32_e32 v2, v122, v2
	v_cvt_pk_bf16_f32 v3, v122, v123
	v_add_f32_e32 v2, v123, v2
	v_add_f32_e32 v2, v124, v2
	v_add_f32_e32 v22, v125, v2
	v_cvt_pk_bf16_f32 v2, v120, v121
	ds_read_b64_tr_b16 v[120:121], v17 offset:31744
	ds_read_b64_tr_b16 v[122:123], v17 offset:32256
	v_mfma_f32_32x32x16_bf16 v[80:95], v[18:21], v[164:167], v[80:95]
	v_add_f32_e32 v4, v126, v22
	v_cvt_pk_bf16_f32 v5, v126, v127
	v_add_f32_e32 v4, v127, v4
	v_add_f32_e32 v140, 0, v4
	v_cvt_pk_bf16_f32 v4, v124, v125
	s_add_i32 s4, s91, s33
	v_lshl_add_u64 v[18:19], v[190:191], 0, s[86:87]
	s_mov_b32 s5, m0
	s_mov_b32 m0, s4
	s_nop 0
	global_load_lds_dwordx4 v[18:19], off
	s_mov_b32 m0, s5
	s_cmp_gt_u32 s92, 1
	v_readlane_b32 s4, v255, 11
	s_cselect_b32 s4, s4, 0
	s_add_i32 s82, s4, s9
	s_lshl_b64 s[4:5], s[82:83], 13
	v_lshl_add_u64 v[18:19], v[14:15], 0, s[4:5]
	s_add_i32 s4, s94, s88
	s_mov_b32 s5, m0
	s_mov_b32 m0, s4
	s_nop 0
	global_load_lds_dwordx4 v[18:19], off
	s_mov_b32 m0, s5
	s_andn2_b64 vcc, exec, s[10:11]
	s_cbranch_vccnz .LBB0_490
	s_add_i32 s4, s90, s9
	s_add_i32 s4, s4, -5
	s_cmp_gt_u32 s4, 7
	s_cbranch_scc1 .LBB0_489
	v_mov_b32_e32 v17, 0
	v_mov_b32_e32 v18, 0
	s_and_saveexec_b64 s[4:5], s[12:13]
	ds_read_b32 v18, v193 offset:124
	s_or_b64 exec, exec, s[4:5]
	s_and_saveexec_b64 s[4:5], s[14:15]
	ds_read_b32 v17, v193 offset:252
	s_or_b64 exec, exec, s[4:5]
	v_mov_b32_e32 v19, 0
	v_mov_b32_e32 v20, 0
	s_and_saveexec_b64 s[4:5], s[16:17]
	ds_read_b32 v20, v193 offset:128
	s_or_b64 exec, exec, s[4:5]
	s_and_saveexec_b64 s[4:5], s[18:19]
	ds_read_b32 v19, v193 offset:256
	s_or_b64 exec, exec, s[4:5]
	v_mov_b32_e32 v21, 0
	v_mov_b32_e32 v22, 0
	s_and_saveexec_b64 s[4:5], s[20:21]
	ds_read_b32 v22, v193 offset:132
	s_or_b64 exec, exec, s[4:5]
	s_and_saveexec_b64 s[4:5], s[22:23]
	ds_read_b32 v21, v193 offset:260
	s_or_b64 exec, exec, s[4:5]
	v_mov_b32_e32 v23, 0
	v_mov_b32_e32 v24, 0
	s_and_saveexec_b64 s[4:5], s[24:25]
	ds_read_b32 v24, v193 offset:136
	s_or_b64 exec, exec, s[4:5]
	s_and_saveexec_b64 s[4:5], s[26:27]
	ds_read_b32 v23, v193 offset:264
	s_or_b64 exec, exec, s[4:5]
	v_mov_b32_e32 v25, 0
	v_mov_b32_e32 v26, 0
	s_and_saveexec_b64 s[4:5], s[28:29]
	ds_read_b32 v26, v193 offset:156
	s_or_b64 exec, exec, s[4:5]
	s_and_saveexec_b64 s[4:5], s[30:31]
	ds_read_b32 v25, v193 offset:284
	s_or_b64 exec, exec, s[4:5]
	v_mov_b32_e32 v27, 0
	v_mov_b32_e32 v28, 0
	s_and_saveexec_b64 s[4:5], s[34:35]
	ds_read_b32 v28, v193 offset:160
	s_or_b64 exec, exec, s[4:5]
	s_and_saveexec_b64 s[4:5], s[36:37]
	ds_read_b32 v27, v193 offset:288
	s_or_b64 exec, exec, s[4:5]
	v_mov_b32_e32 v29, 0
	v_mov_b32_e32 v30, 0
	s_and_saveexec_b64 s[4:5], s[38:39]
	ds_read_b32 v30, v193 offset:164
	s_or_b64 exec, exec, s[4:5]
	s_and_saveexec_b64 s[4:5], s[40:41]
	ds_read_b32 v29, v193 offset:292
	s_or_b64 exec, exec, s[4:5]
	v_mov_b32_e32 v31, 0
	v_mov_b32_e32 v124, 0
	s_and_saveexec_b64 s[4:5], s[42:43]
	ds_read_b32 v124, v193 offset:168
	s_or_b64 exec, exec, s[4:5]
	s_and_saveexec_b64 s[4:5], s[44:45]
	ds_read_b32 v31, v193 offset:296
	s_or_b64 exec, exec, s[4:5]
	v_mov_b32_e32 v125, 0
	v_mov_b32_e32 v126, 0
	s_and_saveexec_b64 s[4:5], s[46:47]
	ds_read_b32 v126, v193 offset:188
	s_or_b64 exec, exec, s[4:5]
	s_and_saveexec_b64 s[4:5], s[48:49]
	ds_read_b32 v125, v193 offset:316
	s_or_b64 exec, exec, s[4:5]
	v_mov_b32_e32 v127, 0
	v_mov_b32_e32 v141, 0
	s_and_saveexec_b64 s[4:5], s[50:51]
	ds_read_b32 v141, v193 offset:192
	s_or_b64 exec, exec, s[4:5]
	s_and_saveexec_b64 s[4:5], s[52:53]
	ds_read_b32 v127, v193 offset:320
	s_or_b64 exec, exec, s[4:5]
	v_mov_b32_e32 v142, 0
	v_mov_b32_e32 v143, 0
	s_and_saveexec_b64 s[4:5], s[54:55]
	ds_read_b32 v143, v193 offset:196
	s_or_b64 exec, exec, s[4:5]
	s_and_saveexec_b64 s[4:5], s[56:57]
	ds_read_b32 v142, v193 offset:324
	s_or_b64 exec, exec, s[4:5]
	v_mov_b32_e32 v152, 0
	v_mov_b32_e32 v153, 0
	s_and_saveexec_b64 s[4:5], s[58:59]
	ds_read_b32 v153, v193 offset:200
	s_or_b64 exec, exec, s[4:5]
	s_and_saveexec_b64 s[4:5], s[60:61]
	ds_read_b32 v152, v193 offset:328
	s_or_b64 exec, exec, s[4:5]
	v_mov_b32_e32 v154, 0
	v_mov_b32_e32 v155, 0
	s_and_saveexec_b64 s[4:5], s[62:63]
	ds_read_b32 v155, v193 offset:220
	s_or_b64 exec, exec, s[4:5]
	s_and_saveexec_b64 s[4:5], s[64:65]
	ds_read_b32 v154, v193 offset:348
	s_or_b64 exec, exec, s[4:5]
	v_mov_b32_e32 v156, 0
	v_mov_b32_e32 v157, 0
	s_and_saveexec_b64 s[4:5], s[66:67]
	ds_read_b32 v157, v193 offset:224
	s_or_b64 exec, exec, s[4:5]
	s_and_saveexec_b64 s[4:5], s[68:69]
	ds_read_b32 v156, v193 offset:352
	s_or_b64 exec, exec, s[4:5]
	v_mov_b32_e32 v158, 0
	v_mov_b32_e32 v159, 0
	s_and_saveexec_b64 s[4:5], s[70:71]
	ds_read_b32 v159, v193 offset:228
	s_or_b64 exec, exec, s[4:5]
	s_and_saveexec_b64 s[4:5], s[72:73]
	ds_read_b32 v158, v193 offset:356
	s_or_b64 exec, exec, s[4:5]
	v_mov_b32_e32 v180, 0
	v_mov_b32_e32 v181, 0
	s_and_saveexec_b64 s[4:5], s[74:75]
	ds_read_b32 v181, v193 offset:232
	s_or_b64 exec, exec, s[4:5]
	s_and_saveexec_b64 s[4:5], s[76:77]
	ds_read_b32 v180, v193 offset:360
	s_or_b64 exec, exec, s[4:5]
	s_waitcnt lgkmcnt(0)
	v_add_f32_e32 v17, v80, v17
	v_cndmask_b32_e64 v80, v16, v17, s[14:15]
	v_add_f32_e32 v17, v97, v20
	v_cndmask_b32_e64 v97, v16, v17, s[16:17]
	v_add_f32_e32 v17, v81, v19
	v_cndmask_b32_e64 v81, v16, v17, s[18:19]
	v_add_f32_e32 v17, v98, v22
	v_cndmask_b32_e64 v98, v16, v17, s[20:21]
	v_add_f32_e32 v17, v82, v21
	v_cndmask_b32_e64 v82, v16, v17, s[22:23]
	v_add_f32_e32 v17, v99, v24
	v_cndmask_b32_e64 v99, v16, v17, s[24:25]
	v_add_f32_e32 v17, v83, v23
	v_cndmask_b32_e64 v83, v16, v17, s[26:27]
	v_add_f32_e32 v17, v100, v26
	v_cndmask_b32_e64 v100, v16, v17, s[28:29]
	v_add_f32_e32 v17, v84, v25
	v_cndmask_b32_e64 v84, v16, v17, s[30:31]
	v_add_f32_e32 v17, v101, v28
	v_cndmask_b32_e64 v101, v16, v17, s[34:35]
	v_add_f32_e32 v17, v85, v27
	v_cndmask_b32_e64 v85, v16, v17, s[36:37]
	v_add_f32_e32 v17, v102, v30
	v_cndmask_b32_e64 v102, v16, v17, s[38:39]
	v_add_f32_e32 v17, v86, v29
	v_cndmask_b32_e64 v86, v16, v17, s[40:41]
	v_add_f32_e32 v17, v103, v124
	v_cndmask_b32_e64 v103, v16, v17, s[42:43]
	v_add_f32_e32 v17, v87, v31
	v_cndmask_b32_e64 v87, v16, v17, s[44:45]
	v_add_f32_e32 v17, v104, v126
	v_cndmask_b32_e64 v104, v16, v17, s[46:47]
	v_add_f32_e32 v17, v88, v125
	v_cndmask_b32_e64 v88, v16, v17, s[48:49]
	v_add_f32_e32 v17, v105, v141
	v_cndmask_b32_e64 v105, v16, v17, s[50:51]
	v_add_f32_e32 v17, v89, v127
	v_cndmask_b32_e64 v89, v16, v17, s[52:53]
	v_add_f32_e32 v17, v106, v143
	v_cndmask_b32_e64 v106, v16, v17, s[54:55]
	v_add_f32_e32 v17, v90, v142
	v_cndmask_b32_e64 v90, v16, v17, s[56:57]
	v_add_f32_e32 v17, v107, v153
	v_cndmask_b32_e64 v107, v16, v17, s[58:59]
	v_add_f32_e32 v17, v91, v152
	v_cndmask_b32_e64 v91, v16, v17, s[60:61]
	v_add_f32_e32 v17, v108, v155
	v_cndmask_b32_e64 v108, v16, v17, s[62:63]
	v_add_f32_e32 v17, v92, v154
	v_cndmask_b32_e64 v92, v16, v17, s[64:65]
	v_add_f32_e32 v17, v109, v157
	v_cndmask_b32_e64 v109, v16, v17, s[66:67]
	v_add_f32_e32 v17, v93, v156
	v_cndmask_b32_e64 v93, v16, v17, s[68:69]
	v_add_f32_e32 v17, v110, v159
	v_cndmask_b32_e64 v110, v16, v17, s[70:71]
	v_add_f32_e32 v17, v94, v158
	v_cndmask_b32_e64 v94, v16, v17, s[72:73]
	v_add_f32_e32 v17, v111, v181
	v_add_f32_e32 v18, v96, v18
	v_cndmask_b32_e64 v111, v16, v17, s[74:75]
	v_add_f32_e32 v17, v95, v180
	v_cndmask_b32_e64 v96, v16, v18, s[12:13]
	v_cndmask_b32_e64 v95, v16, v17, s[76:77]
	s_branch .LBB0_490

.LBB0_502:
	v_add_u32_e32 v17, s4, v216
	ds_read_b64_tr_b16 v[184:185], v17 offset:24576
	ds_read_b64_tr_b16 v[186:187], v17 offset:25088
	s_waitcnt lgkmcnt(9)
	v_mfma_f32_32x32x16_bf16 v[112:127], v[180:183], v[176:179], v[64:79]
	v_add_f32_e32 v2, v96, v97
	v_cvt_pk_bf16_f32 v160, v96, v97
	v_add_f32_e32 v2, v98, v2
	v_cvt_pk_bf16_f32 v161, v98, v99
	v_add_f32_e32 v2, v99, v2
	v_add_f32_e32 v2, v100, v2
	v_add_f32_e32 v2, v101, v2
	ds_read_b64_tr_b16 v[180:181], v17 offset:28672
	ds_read_b64_tr_b16 v[182:183], v17 offset:29184
	s_waitcnt lgkmcnt(10)
	v_mfma_f32_32x32x16_bf16 v[128:143], v[156:159], v[176:179], v[64:79]
	v_add_f32_e32 v2, v102, v2
	v_cvt_pk_bf16_f32 v162, v100, v101
	v_add_f32_e32 v2, v103, v2
	v_cvt_pk_bf16_f32 v163, v102, v103
	v_add_f32_e32 v2, v104, v2
	v_add_f32_e32 v2, v105, v2
	ds_read_b64_tr_b16 v[96:97], v17 offset:25600
	ds_read_b64_tr_b16 v[98:99], v17 offset:26112
	s_waitcnt lgkmcnt(11)
	v_mfma_f32_32x32x16_bf16 v[112:127], v[152:155], v[172:175], v[112:127]
	v_add_f32_e32 v2, v106, v2
	v_cvt_pk_bf16_f32 v10, v104, v105
	v_add_f32_e32 v2, v107, v2
	v_cvt_pk_bf16_f32 v11, v106, v107
	v_add_f32_e32 v2, v108, v2
	v_add_f32_e32 v2, v109, v2
	ds_read_b64_tr_b16 v[100:101], v17 offset:29696
	ds_read_b64_tr_b16 v[102:103], v17 offset:30208
	s_waitcnt lgkmcnt(12)
	v_mfma_f32_32x32x16_bf16 v[128:143], v[148:151], v[172:175], v[128:143]
	v_add_f32_e32 v2, v110, v2
	v_cvt_pk_bf16_f32 v12, v108, v109
	v_add_f32_e32 v2, v111, v2
	v_cvt_pk_bf16_f32 v13, v110, v111
	v_add_f32_e32 v2, v80, v2
	v_add_f32_e32 v2, v81, v2
	ds_read_b64_tr_b16 v[104:105], v17 offset:26624
	ds_read_b64_tr_b16 v[106:107], v17 offset:27136
	s_waitcnt lgkmcnt(13)
	v_mfma_f32_32x32x16_bf16 v[112:127], v[144:147], v[168:171], v[112:127]
	v_add_f32_e32 v2, v82, v2
	v_cvt_pk_bf16_f32 v6, v80, v81
	v_add_f32_e32 v2, v83, v2
	v_cvt_pk_bf16_f32 v7, v82, v83
	v_add_f32_e32 v2, v84, v2
	v_add_f32_e32 v2, v85, v2
	ds_read_b64_tr_b16 v[108:109], v17 offset:30720
	ds_read_b64_tr_b16 v[110:111], v17 offset:31232
	s_waitcnt lgkmcnt(14)
	v_mfma_f32_32x32x16_bf16 v[128:143], v[26:29], v[168:171], v[128:143]
	v_add_f32_e32 v2, v86, v2
	v_cvt_pk_bf16_f32 v8, v84, v85
	v_add_f32_e32 v2, v87, v2
	v_cvt_pk_bf16_f32 v9, v86, v87
	v_add_f32_e32 v2, v88, v2
	v_add_f32_e32 v2, v89, v2
	ds_read_b64_tr_b16 v[188:189], v17 offset:27648
	ds_read_b64_tr_b16 v[190:191], v17 offset:28160
	s_waitcnt lgkmcnt(14)
	v_mfma_f32_32x32x16_bf16 v[112:127], v[22:25], v[164:167], v[112:127]
	v_add_f32_e32 v2, v90, v2
	v_cvt_pk_bf16_f32 v3, v90, v91
	v_add_f32_e32 v2, v91, v2
	v_add_f32_e32 v2, v92, v2
	v_add_f32_e32 v22, v93, v2
	v_cvt_pk_bf16_f32 v2, v88, v89
	ds_read_b64_tr_b16 v[192:193], v17 offset:31744
	ds_read_b64_tr_b16 v[194:195], v17 offset:32256
	v_mfma_f32_32x32x16_bf16 v[128:143], v[18:21], v[164:167], v[128:143]
	v_add_f32_e32 v4, v94, v22
	v_cvt_pk_bf16_f32 v5, v94, v95
	v_add_f32_e32 v4, v95, v4
	v_add_f32_e32 v219, 0, v4
	v_cvt_pk_bf16_f32 v4, v92, v93
	s_cmp_gt_u32 s82, 12
	s_cselect_b64 s[10:11], -1, 0
	s_and_b64 vcc, exec, s[10:11]
	s_cbranch_vccnz .LBB0_504
	s_movk_i32 s6, 0xe000
	s_mov_b32 s7, -1
	s_add_i32 s4, s92, s33
	v_lshl_add_u64 v[18:19], v[196:197], 0, s[6:7]
	s_mov_b32 s5, m0
	s_mov_b32 m0, s4
	s_nop 0
	global_load_lds_dwordx4 v[18:19], off
	s_mov_b32 m0, s5

.LBB0_576:
	v_add_u32_e32 v17, s92, v216
	ds_read_b64_tr_b16 v[180:181], v17 offset:24576
	ds_read_b64_tr_b16 v[182:183], v17 offset:25088
	s_waitcnt lgkmcnt(9)
	v_mfma_f32_32x32x16_bf16 v[96:111], v[112:115], v[176:179], v[64:79]
	v_add_f32_e32 v2, v144, v145
	v_cvt_pk_bf16_f32 v160, v144, v145
	v_add_f32_e32 v2, v146, v2
	v_cvt_pk_bf16_f32 v161, v146, v147
	v_add_f32_e32 v2, v147, v2
	v_add_f32_e32 v2, v148, v2
	v_add_f32_e32 v2, v149, v2
	ds_read_b64_tr_b16 v[140:141], v17 offset:28672
	ds_read_b64_tr_b16 v[142:143], v17 offset:29184
	s_waitcnt lgkmcnt(10)
	v_mfma_f32_32x32x16_bf16 v[112:127], v[128:131], v[176:179], v[64:79]
	v_add_f32_e32 v2, v150, v2
	v_cvt_pk_bf16_f32 v162, v148, v149
	v_add_f32_e32 v2, v151, v2
	v_cvt_pk_bf16_f32 v163, v150, v151
	v_add_f32_e32 v2, v152, v2
	v_add_f32_e32 v2, v153, v2
	ds_read_b64_tr_b16 v[128:129], v17 offset:25600
	ds_read_b64_tr_b16 v[130:131], v17 offset:26112
	s_waitcnt lgkmcnt(11)
	v_mfma_f32_32x32x16_bf16 v[96:111], v[132:135], v[172:175], v[96:111]
	v_add_f32_e32 v2, v154, v2
	v_cvt_pk_bf16_f32 v10, v152, v153
	v_add_f32_e32 v2, v155, v2
	v_cvt_pk_bf16_f32 v11, v154, v155
	v_add_f32_e32 v2, v156, v2
	v_add_f32_e32 v2, v157, v2
	ds_read_b64_tr_b16 v[132:133], v17 offset:29696
	ds_read_b64_tr_b16 v[134:135], v17 offset:30208
	s_waitcnt lgkmcnt(12)
	v_mfma_f32_32x32x16_bf16 v[112:127], v[136:139], v[172:175], v[112:127]
	v_add_f32_e32 v2, v158, v2
	v_cvt_pk_bf16_f32 v12, v156, v157
	v_add_f32_e32 v2, v159, v2
	v_cvt_pk_bf16_f32 v13, v158, v159
	v_add_f32_e32 v2, v80, v2
	v_add_f32_e32 v2, v81, v2
	ds_read_b64_tr_b16 v[136:137], v17 offset:26624
	ds_read_b64_tr_b16 v[138:139], v17 offset:27136
	s_waitcnt lgkmcnt(13)
	v_mfma_f32_32x32x16_bf16 v[96:111], v[184:187], v[168:171], v[96:111]
	v_add_f32_e32 v2, v82, v2
	v_cvt_pk_bf16_f32 v6, v80, v81
	v_add_f32_e32 v2, v83, v2
	v_cvt_pk_bf16_f32 v7, v82, v83
	v_add_f32_e32 v2, v84, v2
	v_add_f32_e32 v2, v85, v2
	ds_read_b64_tr_b16 v[184:185], v17 offset:30720
	ds_read_b64_tr_b16 v[186:187], v17 offset:31232
	s_waitcnt lgkmcnt(14)
	v_mfma_f32_32x32x16_bf16 v[112:127], v[26:29], v[168:171], v[112:127]
	v_add_f32_e32 v2, v86, v2
	v_cvt_pk_bf16_f32 v8, v84, v85
	v_add_f32_e32 v2, v87, v2
	v_cvt_pk_bf16_f32 v9, v86, v87
	v_add_f32_e32 v2, v88, v2
	v_add_f32_e32 v2, v89, v2
	ds_read_b64_tr_b16 v[188:189], v17 offset:27648
	ds_read_b64_tr_b16 v[190:191], v17 offset:28160
	s_waitcnt lgkmcnt(14)
	v_mfma_f32_32x32x16_bf16 v[96:111], v[22:25], v[164:167], v[96:111]
	v_add_f32_e32 v2, v90, v2
	v_cvt_pk_bf16_f32 v3, v90, v91
	v_add_f32_e32 v2, v91, v2
	v_add_f32_e32 v2, v92, v2
	v_add_f32_e32 v22, v93, v2
	v_cvt_pk_bf16_f32 v2, v88, v89
	ds_read_b64_tr_b16 v[192:193], v17 offset:31744
	ds_read_b64_tr_b16 v[194:195], v17 offset:32256
	v_mfma_f32_32x32x16_bf16 v[112:127], v[18:21], v[164:167], v[112:127]
	v_add_f32_e32 v4, v94, v22
	v_cvt_pk_bf16_f32 v5, v94, v95
	v_add_f32_e32 v4, v95, v4
	v_add_f32_e32 v144, 0, v4
	v_cvt_pk_bf16_f32 v4, v92, v93
	s_cmp_gt_u32 s82, 11
	s_cselect_b64 s[8:9], -1, 0
	s_and_b64 vcc, exec, s[8:9]
	s_cbranch_vccnz .LBB0_578
	s_add_i32 s4, s91, s33
	s_mov_b32 s5, m0
	s_mov_b32 m0, s4
	s_nop 0
	global_load_lds_dwordx4 v[196:197], off
	s_mov_b32 m0, s5

.LBB0_662:
	v_readlane_b32 s4, v255, 10
	s_add_i32 s89, s89, s4
	s_max_i32 s4, s89, 4
	s_add_i32 s4, s4, -4
	s_min_u32 s4, s4, 56
	ds_read_b64_tr_b16 v[132:133], v216 offset:40960
	ds_read_b64_tr_b16 v[134:135], v216 offset:41472
	s_waitcnt lgkmcnt(9)
	v_mfma_f32_32x32x16_bf16 v[112:127], v[180:183], v[176:179], v[64:79]
	v_add_f32_e32 v0, v96, v97
	v_cvt_pk_bf16_f32 v160, v96, v97
	v_add_f32_e32 v0, v98, v0
	v_cvt_pk_bf16_f32 v161, v98, v99
	v_add_f32_e32 v0, v99, v0
	v_add_f32_e32 v0, v100, v0
	v_add_f32_e32 v0, v101, v0
	ds_read_b64_tr_b16 v[128:129], v216 offset:45056
	ds_read_b64_tr_b16 v[130:131], v216 offset:45568
	s_waitcnt lgkmcnt(10)
	v_mfma_f32_32x32x16_bf16 v[64:79], v[156:159], v[176:179], v[64:79]
	v_add_f32_e32 v0, v102, v0
	v_cvt_pk_bf16_f32 v162, v100, v101
	v_add_f32_e32 v0, v103, v0
	v_cvt_pk_bf16_f32 v163, v102, v103
	v_add_f32_e32 v0, v104, v0
	v_add_f32_e32 v0, v105, v0
	ds_read_b64_tr_b16 v[136:137], v216 offset:41984
	ds_read_b64_tr_b16 v[138:139], v216 offset:42496
	s_waitcnt lgkmcnt(11)
	v_mfma_f32_32x32x16_bf16 v[112:127], v[152:155], v[172:175], v[112:127]
	v_add_f32_e32 v0, v106, v0
	v_cvt_pk_bf16_f32 v10, v104, v105
	v_add_f32_e32 v0, v107, v0
	v_cvt_pk_bf16_f32 v11, v106, v107
	v_add_f32_e32 v0, v108, v0
	v_add_f32_e32 v0, v109, v0
	ds_read_b64_tr_b16 v[140:141], v216 offset:46080
	ds_read_b64_tr_b16 v[142:143], v216 offset:46592
	s_waitcnt lgkmcnt(12)
	v_mfma_f32_32x32x16_bf16 v[64:79], v[148:151], v[172:175], v[64:79]
	v_add_f32_e32 v0, v110, v0
	v_cvt_pk_bf16_f32 v12, v108, v109
	v_add_f32_e32 v0, v111, v0
	v_cvt_pk_bf16_f32 v13, v110, v111
	v_add_f32_e32 v0, v80, v0
	v_add_f32_e32 v0, v81, v0
	ds_read_b64_tr_b16 v[148:149], v216 offset:43008
	ds_read_b64_tr_b16 v[150:151], v216 offset:43520
	s_waitcnt lgkmcnt(13)
	v_mfma_f32_32x32x16_bf16 v[112:127], v[144:147], v[168:171], v[112:127]
	v_add_f32_e32 v0, v82, v0
	v_cvt_pk_bf16_f32 v6, v80, v81
	v_add_f32_e32 v0, v83, v0
	v_cvt_pk_bf16_f32 v7, v82, v83
	v_add_f32_e32 v0, v84, v0
	v_add_f32_e32 v0, v85, v0
	ds_read_b64_tr_b16 v[144:145], v216 offset:47104
	ds_read_b64_tr_b16 v[146:147], v216 offset:47616
	s_waitcnt lgkmcnt(14)
	v_mfma_f32_32x32x16_bf16 v[64:79], v[26:29], v[168:171], v[64:79]
	v_add_f32_e32 v0, v86, v0
	v_cvt_pk_bf16_f32 v8, v84, v85
	v_add_f32_e32 v0, v87, v0
	v_cvt_pk_bf16_f32 v9, v86, v87
	v_add_f32_e32 v0, v88, v0
	v_add_f32_e32 v0, v89, v0
	ds_read_b64_tr_b16 v[152:153], v216 offset:44032
	ds_read_b64_tr_b16 v[154:155], v216 offset:44544
	s_waitcnt lgkmcnt(14)
	v_mfma_f32_32x32x16_bf16 v[112:127], v[22:25], v[164:167], v[112:127]
	v_add_f32_e32 v0, v90, v0
	v_cvt_pk_bf16_f32 v2, v88, v89
	v_add_f32_e32 v0, v91, v0
	v_cvt_pk_bf16_f32 v3, v90, v91
	v_add_f32_e32 v0, v92, v0
	v_add_f32_e32 v0, v93, v0
	ds_read_b64_tr_b16 v[156:157], v216 offset:48128
	ds_read_b64_tr_b16 v[158:159], v216 offset:48640
	v_mfma_f32_32x32x16_bf16 v[64:79], v[18:21], v[164:167], v[64:79]
	v_add_f32_e32 v0, v94, v0
	v_cvt_pk_bf16_f32 v4, v92, v93
	v_add_f32_e32 v0, v95, v0
	v_cvt_pk_bf16_f32 v5, v94, v95
	v_add_f32_e32 v0, 0, v0
	v_readlane_b32 s5, v255, 11
	s_add_i32 s5, s5, 11
	s_sub_i32 s4, s5, s4
	s_cmp_gt_u32 s4, 7
	s_cbranch_scc1 .LBB0_728
	s_sub_i32 s4, s5, s89
	s_mulk_i32 s4, 0x7c
	s_add_i32 s4, s4, 0
	v_lshlrev_b32_e32 v14, 2, v214
	v_sub_u32_e32 v14, s4, v14
	v_add_u32_e32 v15, 0x16000, v14
	v_mov_b32_e32 v14, 0
	v_lshl_add_u32 v17, v217, 2, v15
	v_mov_b32_e32 v15, 0
	s_and_saveexec_b64 s[4:5], s[12:13]
	v_readlane_b32 s90, v255, 15
	v_readlane_b32 s92, v254, 58
	s_movk_i32 s82, 0x1000
	v_readlane_b32 s33, v255, 12
	v_readlane_b32 s91, v255, 16
	ds_read_b32 v15, v17 offset:928
	s_or_b64 exec, exec, s[4:5]
	s_and_saveexec_b64 s[4:5], s[14:15]
	ds_read_b32 v14, v17 offset:1056
	s_or_b64 exec, exec, s[4:5]
	v_mov_b32_e32 v18, 0
	v_mov_b32_e32 v19, 0
	s_and_saveexec_b64 s[4:5], s[16:17]
	v_readlane_b32 s88, v255, 17
	v_readlane_b32 s89, v255, 18
	ds_read_b32 v19, v17 offset:932
	s_or_b64 exec, exec, s[4:5]
	s_and_saveexec_b64 s[4:5], s[18:19]
	ds_read_b32 v18, v17 offset:1060
	s_or_b64 exec, exec, s[4:5]
	v_mov_b32_e32 v20, 0
	v_mov_b32_e32 v21, 0
	s_and_saveexec_b64 s[4:5], s[20:21]
	ds_read_b32 v21, v17 offset:936
	s_or_b64 exec, exec, s[4:5]
	s_and_saveexec_b64 s[4:5], s[22:23]
	ds_read_b32 v20, v17 offset:1064
	s_or_b64 exec, exec, s[4:5]
	v_mov_b32_e32 v22, 0
	v_mov_b32_e32 v23, 0
	s_and_saveexec_b64 s[4:5], s[24:25]
	ds_read_b32 v23, v17 offset:940
	s_or_b64 exec, exec, s[4:5]
	s_and_saveexec_b64 s[4:5], s[26:27]
	ds_read_b32 v22, v17 offset:1068
	s_or_b64 exec, exec, s[4:5]
	v_mov_b32_e32 v24, 0
	v_mov_b32_e32 v25, 0
	s_and_saveexec_b64 s[4:5], s[28:29]
	ds_read_b32 v25, v17 offset:960
	s_or_b64 exec, exec, s[4:5]
	s_and_saveexec_b64 s[4:5], s[30:31]
	ds_read_b32 v24, v17 offset:1088
	s_or_b64 exec, exec, s[4:5]
	v_mov_b32_e32 v26, 0
	v_mov_b32_e32 v27, 0
	s_and_saveexec_b64 s[4:5], s[34:35]
	ds_read_b32 v27, v17 offset:964
	s_or_b64 exec, exec, s[4:5]
	s_and_saveexec_b64 s[4:5], s[36:37]
	ds_read_b32 v26, v17 offset:1092
	s_or_b64 exec, exec, s[4:5]
	v_mov_b32_e32 v28, 0
	v_mov_b32_e32 v29, 0
	s_and_saveexec_b64 s[4:5], s[38:39]
	ds_read_b32 v29, v17 offset:968
	s_or_b64 exec, exec, s[4:5]
	s_and_saveexec_b64 s[4:5], s[40:41]
	ds_read_b32 v28, v17 offset:1096
	s_or_b64 exec, exec, s[4:5]
	v_mov_b32_e32 v30, 0
	v_mov_b32_e32 v31, 0
	s_and_saveexec_b64 s[4:5], s[42:43]
	ds_read_b32 v31, v17 offset:972
	s_or_b64 exec, exec, s[4:5]
	s_and_saveexec_b64 s[4:5], s[44:45]
	ds_read_b32 v30, v17 offset:1100
	s_or_b64 exec, exec, s[4:5]
	v_mov_b32_e32 v89, 0
	v_mov_b32_e32 v88, 0
	s_and_saveexec_b64 s[4:5], s[46:47]
	ds_read_b32 v88, v17 offset:992
	s_or_b64 exec, exec, s[4:5]
	s_and_saveexec_b64 s[4:5], s[48:49]
	ds_read_b32 v89, v17 offset:1120
	s_or_b64 exec, exec, s[4:5]
	v_mov_b32_e32 v90, 0
	v_mov_b32_e32 v91, 0
	s_and_saveexec_b64 s[4:5], s[50:51]
	ds_read_b32 v91, v17 offset:996
	s_or_b64 exec, exec, s[4:5]
	s_and_saveexec_b64 s[4:5], s[52:53]
	ds_read_b32 v90, v17 offset:1124
	s_or_b64 exec, exec, s[4:5]
	v_mov_b32_e32 v92, 0
	v_mov_b32_e32 v93, 0
	s_and_saveexec_b64 s[4:5], s[54:55]
	ds_read_b32 v93, v17 offset:1000
	s_or_b64 exec, exec, s[4:5]
	s_and_saveexec_b64 s[4:5], s[56:57]
	ds_read_b32 v92, v17 offset:1128
	s_or_b64 exec, exec, s[4:5]
	v_mov_b32_e32 v94, 0
	v_mov_b32_e32 v95, 0
	s_and_saveexec_b64 s[4:5], s[58:59]
	ds_read_b32 v95, v17 offset:1004
	s_or_b64 exec, exec, s[4:5]
	s_and_saveexec_b64 s[4:5], s[60:61]
	ds_read_b32 v94, v17 offset:1132
	s_or_b64 exec, exec, s[4:5]
	v_mov_b32_e32 v96, 0
	v_mov_b32_e32 v97, 0
	s_and_saveexec_b64 s[4:5], s[62:63]
	ds_read_b32 v97, v17 offset:1024
	s_or_b64 exec, exec, s[4:5]
	s_and_saveexec_b64 s[4:5], s[64:65]
	ds_read_b32 v96, v17 offset:1152
	s_or_b64 exec, exec, s[4:5]
	v_mov_b32_e32 v98, 0
	v_mov_b32_e32 v99, 0
	s_and_saveexec_b64 s[4:5], s[66:67]
	ds_read_b32 v99, v17 offset:1028
	s_or_b64 exec, exec, s[4:5]
	s_and_saveexec_b64 s[4:5], s[68:69]
	ds_read_b32 v98, v17 offset:1156
	s_or_b64 exec, exec, s[4:5]
	v_mov_b32_e32 v100, 0
	v_mov_b32_e32 v101, 0
	s_and_saveexec_b64 s[4:5], s[70:71]
	ds_read_b32 v101, v17 offset:1032
	s_or_b64 exec, exec, s[4:5]
	s_and_saveexec_b64 s[4:5], s[72:73]
	ds_read_b32 v100, v17 offset:1160
	s_or_b64 exec, exec, s[4:5]
	v_mov_b32_e32 v102, 0
	v_mov_b32_e32 v103, 0
	s_and_saveexec_b64 s[4:5], s[74:75]
	ds_read_b32 v103, v17 offset:1036
	s_or_b64 exec, exec, s[4:5]
	s_and_saveexec_b64 s[4:5], s[76:77]
	ds_read_b32 v102, v17 offset:1164
	s_or_b64 exec, exec, s[4:5]
	s_waitcnt lgkmcnt(0)
	v_add_f32_e32 v14, v64, v14
	v_cndmask_b32_e64 v64, v16, v14, s[14:15]
	v_add_f32_e32 v14, v113, v19
	v_cndmask_b32_e64 v81, v16, v14, s[16:17]
	v_add_f32_e32 v14, v65, v18
	v_cndmask_b32_e64 v65, v16, v14, s[18:19]
	v_add_f32_e32 v14, v114, v21
	v_cndmask_b32_e64 v82, v16, v14, s[20:21]
	v_add_f32_e32 v14, v66, v20
	v_cndmask_b32_e64 v66, v16, v14, s[22:23]
	v_add_f32_e32 v14, v115, v23
	v_cndmask_b32_e64 v83, v16, v14, s[24:25]
	v_add_f32_e32 v14, v67, v22
	v_cndmask_b32_e64 v67, v16, v14, s[26:27]
	v_add_f32_e32 v14, v116, v25
	v_cndmask_b32_e64 v84, v16, v14, s[28:29]
	v_add_f32_e32 v14, v68, v24
	v_cndmask_b32_e64 v68, v16, v14, s[30:31]
	v_add_f32_e32 v14, v117, v27
	v_cndmask_b32_e64 v85, v16, v14, s[34:35]
	v_add_f32_e32 v14, v69, v26
	v_cndmask_b32_e64 v69, v16, v14, s[36:37]
	v_add_f32_e32 v14, v118, v29
	v_cndmask_b32_e64 v86, v16, v14, s[38:39]
	v_add_f32_e32 v14, v70, v28
	v_cndmask_b32_e64 v70, v16, v14, s[40:41]
	v_add_f32_e32 v14, v119, v31
	v_cndmask_b32_e64 v87, v16, v14, s[42:43]
	v_add_f32_e32 v14, v71, v30
	v_cndmask_b32_e64 v71, v16, v14, s[44:45]
	v_add_f32_e32 v14, v120, v88
	v_cndmask_b32_e64 v88, v16, v14, s[46:47]
	v_add_f32_e32 v14, v72, v89
	v_cndmask_b32_e64 v72, v16, v14, s[48:49]
	v_add_f32_e32 v14, v121, v91
	v_cndmask_b32_e64 v89, v16, v14, s[50:51]
	v_add_f32_e32 v14, v73, v90
	v_cndmask_b32_e64 v73, v16, v14, s[52:53]
	v_add_f32_e32 v14, v122, v93
	v_cndmask_b32_e64 v90, v16, v14, s[54:55]
	v_add_f32_e32 v14, v74, v92
	v_cndmask_b32_e64 v74, v16, v14, s[56:57]
	v_add_f32_e32 v14, v123, v95
	v_cndmask_b32_e64 v91, v16, v14, s[58:59]
	v_add_f32_e32 v14, v75, v94
	v_cndmask_b32_e64 v75, v16, v14, s[60:61]
	v_add_f32_e32 v14, v124, v97
	v_cndmask_b32_e64 v92, v16, v14, s[62:63]
	v_add_f32_e32 v14, v76, v96
	v_cndmask_b32_e64 v76, v16, v14, s[64:65]
	v_add_f32_e32 v14, v125, v99
	v_cndmask_b32_e64 v93, v16, v14, s[66:67]
	v_add_f32_e32 v14, v77, v98
	v_cndmask_b32_e64 v77, v16, v14, s[68:69]
	v_add_f32_e32 v14, v126, v101
	v_cndmask_b32_e64 v94, v16, v14, s[70:71]
	v_add_f32_e32 v14, v78, v100
	v_cndmask_b32_e64 v78, v16, v14, s[72:73]
	v_add_f32_e32 v14, v127, v103
	v_add_f32_e32 v15, v112, v15
	v_cndmask_b32_e64 v95, v16, v14, s[74:75]
	v_add_f32_e32 v14, v79, v102
	v_cndmask_b32_e64 v80, v16, v15, s[12:13]
	v_cndmask_b32_e64 v79, v16, v14, s[76:77]
	s_branch .LBB0_729

; __device__ __forceinline__ int crow(int r,int hi){return (r&3)+8*(r>>2)+4*hi;}
; #define SBAR() __builtin_amdgcn_sched_barrier(0)
;   #define PKW(P,B) cvtpk_s(P[B],P[B+1])
;     ...
;   { float sacc=pB0[0]+pB0[1]; _Pragma("unroll") for(int r=2;r<16;++r)sacc+=pB0[r]; _Pragma("unroll") for(int r=0;r<16;++r)sacc+=pB1[r]; l_reg+=sacc;
;     pw0=(u32x4){PKW(pB0,0),PKW(pB0,2),PKW(pB0,4),PKW(pB0,6)};pw1=(u32x4){PKW(pB0,8),PKW(pB0,10),PKW(pB0,12),PKW(pB0,14)};pw2=(u32x4){PKW(pB1,0),PKW(pB1,2),PKW(pB1,4),PKW(pB1,6)};pw3=(u32x4){PKW(pB1,8),PKW(pB1,10),PKW(pB1,12),PKW(pB1,14)};
;     SBAR(); pv(o,vb0+sl_cur,PAF(0),PAF(1),PAF(2),PAF(3)); if constexpr(DV2) pv(o+2,vb0+(LDS_V2-LDS_V)+sl_cur,PAF(0),PAF(1),PAF(2),PAF(3)); }
;     ...
;   {auto rr=__builtin_amdgcn_permlane32_swap(__float_as_uint(l_reg),__float_as_uint(l_reg),false,false);l_reg=__uint_as_float(rr[0])+__uint_as_float(rr[1]);}
;   if(hi==0)wsf[32+r32]=l_reg;asm volatile("s_waitcnt lgkmcnt(0)":::"memory");
;   float rli[16];
;   #pragma unroll
;   for(int r=0;r<16;++r)rli[r]=__builtin_amdgcn_rcpf(wsf[32+crow(r,hi)]);
.LBB0_732:
	v_add_f32_e32 v4, v80, v81
	v_add_f32_e32 v4, v82, v4
	v_add_f32_e32 v4, v83, v4
	v_add_f32_e32 v4, v84, v4
	v_add_f32_e32 v4, v85, v4
	v_add_f32_e32 v4, v86, v4
	v_add_f32_e32 v4, v87, v4
	v_add_f32_e32 v4, v88, v4
	v_add_f32_e32 v4, v89, v4
	v_add_f32_e32 v4, v90, v4
	v_add_f32_e32 v4, v91, v4
	v_add_f32_e32 v4, v92, v4
	v_add_f32_e32 v4, v93, v4
	v_add_f32_e32 v4, v94, v4
	v_add_f32_e32 v4, v95, v4
	v_add_f32_e32 v4, v64, v4
	v_add_f32_e32 v4, v65, v4
	v_add_f32_e32 v4, v66, v4
	v_add_f32_e32 v4, v67, v4
	v_add_f32_e32 v4, v68, v4
	v_add_f32_e32 v4, v69, v4
	v_add_f32_e32 v4, v70, v4
	v_add_f32_e32 v4, v71, v4
	v_add_f32_e32 v4, v72, v4
	v_add_f32_e32 v4, v73, v4
	v_add_f32_e32 v4, v74, v4
	v_add_f32_e32 v4, v75, v4
	s_cmp_lg_u32 0, -1
	v_add_f32_e32 v4, v76, v4
	s_cselect_b32 s4, 0, 0
	v_add_f32_e32 v4, v77, v4
	s_addk_i32 s4, 0x6000
	v_add_f32_e32 v4, v78, v4
	v_add_u32_e32 v3, s4, v207
	v_add_f32_e32 v4, v79, v4
	v_readlane_b32 s34, v255, 13
	v_readlane_b32 s35, v255, 14
	v_readlane_b32 s8, v255, 9
	v_add3_u32 v3, v3, v206, v208
	v_add_f32_e32 v0, v0, v4
	v_cvt_pk_bf16_f32 v4, v80, v81
	v_cvt_pk_bf16_f32 v5, v82, v83
	v_cvt_pk_bf16_f32 v6, v84, v85
	v_cvt_pk_bf16_f32 v7, v86, v87
	v_cvt_pk_bf16_f32 v8, v88, v89
	v_cvt_pk_bf16_f32 v9, v90, v91
	v_cvt_pk_bf16_f32 v10, v92, v93
	v_cvt_pk_bf16_f32 v11, v94, v95
	v_cvt_pk_bf16_f32 v12, v64, v65
	v_cvt_pk_bf16_f32 v13, v66, v67
	v_cvt_pk_bf16_f32 v14, v68, v69
	v_cvt_pk_bf16_f32 v15, v70, v71
	v_cvt_pk_bf16_f32 v18, v72, v73
	v_cvt_pk_bf16_f32 v19, v74, v75
	v_cvt_pk_bf16_f32 v20, v76, v77
	v_cvt_pk_bf16_f32 v21, v78, v79
	ds_read_b64_tr_b16 v[22:23],v3 offset:0
	ds_read_b64_tr_b16 v[24:25],v3 offset:512
	ds_read_b64_tr_b16 v[26:27],v3 offset:1024
	ds_read_b64_tr_b16 v[28:29],v3 offset:1536
	ds_read_b64_tr_b16 v[64:65],v3 offset:2048
	ds_read_b64_tr_b16 v[66:67],v3 offset:2560
	ds_read_b64_tr_b16 v[68:69],v3 offset:3072
	ds_read_b64_tr_b16 v[70:71],v3 offset:3584
	s_waitcnt lgkmcnt(0)
	s_nop 0
	v_mfma_f32_32x32x16_bf16 v[32:47], v[4:7], v[22:25], v[32:47]
	ds_read_b64_tr_b16 v[22:23],v3 offset:4096
	ds_read_b64_tr_b16 v[24:25],v3 offset:4608
	v_mfma_f32_32x32x16_bf16 v[32:47], v[8:11], v[26:29], v[32:47]
	ds_read_b64_tr_b16 v[26:27],v3 offset:5120
	ds_read_b64_tr_b16 v[28:29],v3 offset:5632
	v_mfma_f32_32x32x16_bf16 v[32:47], v[12:15], v[64:67], v[32:47]
	ds_read_b64_tr_b16 v[64:65],v3 offset:6144
	ds_read_b64_tr_b16 v[66:67],v3 offset:6656
	v_mfma_f32_32x32x16_bf16 v[32:47], v[18:21], v[68:71], v[32:47]
	ds_read_b64_tr_b16 v[68:69],v3 offset:7168
	ds_read_b64_tr_b16 v[70:71],v3 offset:7680
	s_waitcnt lgkmcnt(0)
	v_mfma_f32_32x32x16_bf16 v[48:63], v[4:7], v[22:25], v[48:63]
	v_mov_b32_e32 v3, v0
	s_nop 1
	v_permlane32_swap_b32_e32 v0, v3
	v_mfma_f32_32x32x16_bf16 v[48:63], v[8:11], v[26:29], v[48:63]
	v_mfma_f32_32x32x16_bf16 v[48:63], v[12:15], v[64:67], v[48:63]
	v_mfma_f32_32x32x16_bf16 v[48:63], v[18:21], v[68:71], v[48:63]
	s_mov_b64 s[4:5], exec
	v_readlane_b32 s6, v255, 19
	v_readlane_b32 s7, v255, 20
	s_and_b64 s[6:7], s[4:5], s[6:7]
	s_mov_b64 exec, s[6:7]
	v_add_f32_e32 v0, v0, v3
	ds_write_b32 v212, v0 offset:49280
	s_or_b64 exec, exec, s[4:5]
	s_lshl_b32 s4, s8, 19
	v_readlane_b32 s5, v254, 55
	v_readlane_b32 s8, v254, 25
	s_or_b32 s4, s4, s5
	v_readlane_b32 s14, v254, 31
	s_waitcnt lgkmcnt(0)
	v_readlane_b32 s15, v254, 32
	s_add_u32 s5, s14, s4
	ds_read_b128 v[4:7], v2 offset:49280
	ds_read_b128 v[8:11], v2 offset:49312
	v_readlane_b32 s16, v254, 33
	s_addc_u32 s6, s15, 0
	v_readlane_b32 s17, v254, 34
	s_add_u32 s4, s16, s4
	v_readlane_b32 s8, v255, 8
	s_addc_u32 s7, s17, 0
	s_lshl_b32 s8, s8, 7
	v_readlane_b32 s10, v254, 27
	v_readlane_b32 s12, v254, 29
	v_readlane_b32 s13, v254, 30
	s_add_u32 s5, s5, s8
	s_addc_u32 s10, s6, 0
	s_waitcnt lgkmcnt(1)
	v_rcp_f32_e32 v0, v4
	v_rcp_f32_e32 v3, v5
	v_rcp_f32_e32 v12, v6
	v_rcp_f32_e32 v13, v7
	s_waitcnt lgkmcnt(0)
	v_rcp_f32_e32 v14, v8
	ds_read_b128 v[4:7], v2 offset:49344
	v_rcp_f32_e32 v15, v9
	v_rcp_f32_e32 v17, v10
	v_rcp_f32_e32 v18, v11
	ds_read_b128 v[8:11], v2 offset:49376
	v_readlane_b32 s12, v255, 21
	v_readlane_b32 s9, v254, 26
	s_add_u32 s4, s4, s8
	v_readlane_b32 s13, v255, 22
	s_addc_u32 s7, s7, 0
	s_lshl_b64 s[8:9], s[12:13], 16
	s_add_u32 s6, s4, s8
	v_readlane_b32 s11, v254, 28
	s_addc_u32 s7, s7, s9
	s_lshl_b32 s4, s12, 12
	s_waitcnt lgkmcnt(1)
	v_rcp_f32_e32 v2, v4
	v_rcp_f32_e32 v4, v5
	v_rcp_f32_e32 v5, v6
	v_rcp_f32_e32 v6, v7
	s_waitcnt lgkmcnt(0)
; __device__ __forceinline__ int crow(int r,int hi){return (r&3)+8*(r>>2)+4*hi;}
;     ...
;   for(int r=0;r<16;++r)rli[r]=__builtin_amdgcn_rcpf(wsf[32+crow(r,hi)]);
;   if constexpr(DV2){ float*Orw=Oraw+(long)wid*QBLK*128;
;     #pragma unroll
;     for(int r=0;r<16;++r){const int orow=crow(r,hi);
;       #pragma unroll
;       for(int d0=0;d0<4;++d0) Orw[orow*128+d0*32+r32]=o[d0][r]*rli[r];}
;   } else {
;   bf16*Ow=OGu+(long)wid*QBLK*1024; const bf16*Zw=SZu+(long)wid*QBLK*1024;
;   { bf16*stg=(bf16*)(shm+LDS_OST)+wid*2048;
;     #pragma unroll
;     for(int r=0;r<16;++r){const int orow=crow(r,hi);
;       #pragma unroll
;       for(int d0=0;d0<2;++d0) stg[orow*64+d0*32+r32]=(bf16)(pk_bf16(o[d0][r]*rli[r],0.f)&0xffffu);}
;     asm volatile("s_waitcnt lgkmcnt(0)":::"memory");
;     #pragma unroll
;     for(int i=0;i<4;++i){const int row=i*8+(lane>>3),ch=lane&7; const u32x4 v=*(const u32x4*)(stg+row*64+ch*8); const u32x4 z=*(const u32x4*)(Zw+(long)row*1024+ch*8); u32x4 g;
	v_rcp_f32_e32 v7, v8
	v_rcp_f32_e32 v8, v9
	v_rcp_f32_e32 v9, v10
	v_rcp_f32_e32 v10, v11
	s_add_i32 s11, s4, 0
	v_lshlrev_b32_e32 v11, 9, v205
	v_lshlrev_b32_e32 v19, 1, v204
	v_add3_u32 v11, s11, v11, v19
	v_mul_f32_e32 v19, v32, v0
	v_mul_f32_e32 v0, v48, v0
	v_cvt_pk_bf16_f32 v0, v0, v1
	ds_write_b16 v11, v0 offset:51264
	v_mul_f32_e32 v0, v33, v3
	v_cvt_pk_bf16_f32 v0, v0, v1
	ds_write_b16 v11, v0 offset:51328
	v_mul_f32_e32 v0, v49, v3
	v_cvt_pk_bf16_f32 v0, v0, v1
	ds_write_b16 v11, v0 offset:51392
	v_mul_f32_e32 v0, v34, v12
	v_cvt_pk_bf16_f32 v0, v0, v1
	ds_write_b16 v11, v0 offset:51456
	v_mul_f32_e32 v0, v50, v12
	v_cvt_pk_bf16_f32 v0, v0, v1
	ds_write_b16 v11, v0 offset:51520
	v_mul_f32_e32 v0, v35, v13
	v_cvt_pk_bf16_f32 v0, v0, v1
	ds_write_b16 v11, v0 offset:51584
	v_mul_f32_e32 v0, v51, v13
	v_cvt_pk_bf16_f32 v0, v0, v1
	ds_write_b16 v11, v0 offset:51648
	v_mul_f32_e32 v0, v36, v14
	v_cvt_pk_bf16_f32 v0, v0, v1
	ds_write_b16 v11, v0 offset:52224
	v_mul_f32_e32 v0, v52, v14
	v_cvt_pk_bf16_f32 v0, v0, v1
	ds_write_b16 v11, v0 offset:52288
	v_mul_f32_e32 v0, v37, v15
	v_cvt_pk_bf16_f32 v0, v0, v1
	ds_write_b16 v11, v0 offset:52352
	v_mul_f32_e32 v0, v53, v15
	v_cvt_pk_bf16_f32 v0, v0, v1
	ds_write_b16 v11, v0 offset:52416
	v_mul_f32_e32 v0, v38, v17
	v_cvt_pk_bf16_f32 v0, v0, v1
	ds_write_b16 v11, v0 offset:52480
	v_mul_f32_e32 v0, v54, v17
	v_cvt_pk_bf16_f32 v0, v0, v1
	ds_write_b16 v11, v0 offset:52544
	v_mul_f32_e32 v0, v39, v18
	v_cvt_pk_bf16_f32 v0, v0, v1
	ds_write_b16 v11, v0 offset:52608
	v_mul_f32_e32 v0, v55, v18
	v_cvt_pk_bf16_f32 v0, v0, v1
	ds_write_b16 v11, v0 offset:52672
	v_mul_f32_e32 v0, v40, v2
	v_cvt_pk_bf16_f32 v0, v0, v1
	ds_write_b16 v11, v0 offset:53248
	v_mul_f32_e32 v0, v56, v2
	v_cvt_pk_bf16_f32 v0, v0, v1
	ds_write_b16 v11, v0 offset:53312
	v_mul_f32_e32 v0, v41, v4
	v_cvt_pk_bf16_f32 v0, v0, v1
	ds_write_b16 v11, v0 offset:53376
	v_mul_f32_e32 v0, v57, v4
	v_cvt_pk_bf16_f32 v0, v0, v1
	ds_write_b16 v11, v0 offset:53440
	v_mul_f32_e32 v0, v42, v5
	v_cvt_pk_bf16_f32 v0, v0, v1
	ds_write_b16 v11, v0 offset:53504
	v_mul_f32_e32 v0, v58, v5
	v_cvt_pk_bf16_f32 v0, v0, v1
	ds_write_b16 v11, v0 offset:53568
	v_mul_f32_e32 v0, v43, v6
	v_cvt_pk_bf16_f32 v0, v0, v1
	ds_write_b16 v11, v0 offset:53632
	v_mul_f32_e32 v0, v59, v6
	v_cvt_pk_bf16_f32 v0, v0, v1
	ds_write_b16 v11, v0 offset:53696
	v_mul_f32_e32 v0, v44, v7
	v_cvt_pk_bf16_f32 v0, v0, v1
	ds_write_b16 v11, v0 offset:54272
	v_mul_f32_e32 v0, v60, v7
	v_cvt_pk_bf16_f32 v0, v0, v1
	ds_write_b16 v11, v0 offset:54336
	v_mul_f32_e32 v0, v45, v8
	v_cvt_pk_bf16_f32 v0, v0, v1
	ds_write_b16 v11, v0 offset:54400
	v_mul_f32_e32 v0, v61, v8
	v_cvt_pk_bf16_f32 v0, v0, v1
	ds_write_b16 v11, v0 offset:54464
	v_mul_f32_e32 v0, v46, v9
	v_cvt_pk_bf16_f32 v0, v0, v1
	ds_write_b16 v11, v0 offset:54528
	v_mul_f32_e32 v0, v62, v9
	v_cvt_pk_bf16_f32 v0, v0, v1
	ds_write_b16 v11, v0 offset:54592
	v_mul_f32_e32 v0, v47, v10
	v_cvt_pk_bf16_f32 v0, v0, v1
	ds_write_b16 v11, v0 offset:54656
	v_mul_f32_e32 v0, v63, v10
	v_cvt_pk_bf16_f32 v0, v0, v1
	ds_write_b16 v11, v0 offset:54720
	s_add_u32 s4, s5, s8
	v_lshlrev_b32_e32 v0, 1, v203
	s_addc_u32 s5, s10, s9
	v_lshrrev_b32_e32 v14, 3, v202
	v_and_b32_e32 v0, 0x70, v0
	v_cvt_pk_bf16_f32 v19, v19, v1
	ds_write_b16 v11, v19 offset:51200
	v_add_u32_e32 v17, s11, v0
	v_lshl_add_u64 v[10:11], s[4:5], 0, v[0:1]
	v_lshl_add_u64 v[12:13], s[6:7], 0, v[0:1]
	v_mov_b32_e32 v117, 0
	v_lshlrev_b32_e32 v116, 11, v14
	v_lshl_add_u64 v[118:119], v[10:11], 0, v[116:117]
	global_load_dwordx4 v[100:103], v[118:119], off
	v_or_b32_e32 v116, 8, v14
	v_lshlrev_b32_e32 v116, 11, v116
	v_lshl_add_u64 v[118:119], v[10:11], 0, v[116:117]
	global_load_dwordx4 v[104:107], v[118:119], off
	v_or_b32_e32 v116, 16, v14
	v_lshlrev_b32_e32 v116, 11, v116
	v_lshl_add_u64 v[118:119], v[10:11], 0, v[116:117]
	global_load_dwordx4 v[108:111], v[118:119], off
	v_or_b32_e32 v116, 24, v14
	v_lshlrev_b32_e32 v116, 11, v116
	v_lshl_add_u64 v[118:119], v[10:11], 0, v[116:117]
	global_load_dwordx4 v[112:115], v[118:119], off
	v_lshlrev_b32_e32 v0, 11, v14
	s_waitcnt lgkmcnt(0)
	v_lshl_add_u64 v[2:3], v[10:11], 0, v[0:1]
	v_lshl_add_u32 v6, v14, 7, v17
	ds_read_b128 v[6:9], v6 offset:51200
	s_mov_b64 s[4:5], 0
	v_readlane_b32 s18, v254, 35
	v_readlane_b32 s19, v254, 36
	v_readlane_b32 s20, v254, 37
	s_waitcnt lgkmcnt(0)
	v_lshlrev_b32_e32 v15, 16, v6
	v_and_b32_e32 v6, 0xffff0000, v6
	v_readlane_b32 s21, v254, 38
	v_readlane_b32 s22, v254, 39
	v_readlane_b32 s23, v254, 40
	s_waitcnt vmcnt(3)
;     ...
;     for(int i=0;i<4;++i){const int row=i*8+(lane>>3),ch=lane&7; const u32x4 v=*(const u32x4*)(stg+row*64+ch*8); const u32x4 z=*(const u32x4*)(Zw+(long)row*1024+ch*8); u32x4 g;
;       #pragma unroll
;       for(int e=0;e<4;++e){ const float a0=__uint_as_float(v[e]<<16)*__uint_as_float(z[e]<<16), a1=__uint_as_float(v[e]&0xffff0000u)*__uint_as_float(z[e]&0xffff0000u); g[e]=pk_bf16(a0,a1); }
;       *(u32x4*)(Ow+(long)row*1024+ch*8)=g;} }
;   }
;   asm volatile("s_waitcnt lgkmcnt(0)\n\ts_barrier":::"memory");
	v_lshlrev_b32_e32 v18, 16, v100
	v_and_b32_e32 v2, 0xffff0000, v100
	v_mul_f32_e32 v15, v18, v15
	v_mul_f32_e32 v2, v2, v6
	v_cvt_pk_bf16_f32 v2, v15, v2
	v_lshlrev_b32_e32 v6, 16, v7
	v_lshlrev_b32_e32 v15, 16, v101
	v_and_b32_e32 v3, 0xffff0000, v101
	v_and_b32_e32 v7, 0xffff0000, v7
	v_mul_f32_e32 v6, v15, v6
	v_mul_f32_e32 v3, v3, v7
	v_cvt_pk_bf16_f32 v3, v6, v3
	v_lshlrev_b32_e32 v6, 16, v8
	v_lshlrev_b32_e32 v7, 16, v102
	v_mul_f32_e32 v6, v7, v6
	v_and_b32_e32 v4, 0xffff0000, v102
	v_and_b32_e32 v7, 0xffff0000, v8
	v_mul_f32_e32 v4, v4, v7
	v_cvt_pk_bf16_f32 v4, v6, v4
	v_lshlrev_b32_e32 v6, 16, v9
	v_lshlrev_b32_e32 v7, 16, v103
	v_mul_f32_e32 v6, v7, v6
	v_and_b32_e32 v5, 0xffff0000, v103
	v_and_b32_e32 v7, 0xffff0000, v9
	v_mul_f32_e32 v5, v5, v7
	v_cvt_pk_bf16_f32 v5, v6, v5
	v_lshl_add_u64 v[6:7], v[12:13], 0, v[0:1]
	global_store_dwordx4 v[6:7], v[2:5], off
	v_or_b32_e32 v6, 8, v14
	v_lshlrev_b32_e32 v0, 11, v6
	v_lshl_add_u64 v[2:3], v[10:11], 0, v[0:1]
	v_lshl_add_u32 v6, v6, 7, v17
	ds_read_b128 v[6:9], v6 offset:51200
	s_waitcnt lgkmcnt(0)
	v_lshlrev_b32_e32 v15, 16, v6
	v_and_b32_e32 v6, 0xffff0000, v6
	s_waitcnt vmcnt(3)
	v_lshlrev_b32_e32 v18, 16, v104
	v_and_b32_e32 v2, 0xffff0000, v104
	v_mul_f32_e32 v15, v18, v15
	v_mul_f32_e32 v2, v2, v6
	v_cvt_pk_bf16_f32 v2, v15, v2
	v_lshlrev_b32_e32 v6, 16, v7
	v_lshlrev_b32_e32 v15, 16, v105
	v_and_b32_e32 v3, 0xffff0000, v105
	v_and_b32_e32 v7, 0xffff0000, v7
	v_mul_f32_e32 v6, v15, v6
	v_mul_f32_e32 v3, v3, v7
	v_cvt_pk_bf16_f32 v3, v6, v3
	v_lshlrev_b32_e32 v6, 16, v8
	v_lshlrev_b32_e32 v7, 16, v106
	v_mul_f32_e32 v6, v7, v6
	v_and_b32_e32 v4, 0xffff0000, v106
	v_and_b32_e32 v7, 0xffff0000, v8
	v_mul_f32_e32 v4, v4, v7
	v_cvt_pk_bf16_f32 v4, v6, v4
	v_lshlrev_b32_e32 v6, 16, v9
	v_lshlrev_b32_e32 v7, 16, v107
	v_mul_f32_e32 v6, v7, v6
	v_and_b32_e32 v5, 0xffff0000, v107
	v_and_b32_e32 v7, 0xffff0000, v9
	v_mul_f32_e32 v5, v5, v7
	v_cvt_pk_bf16_f32 v5, v6, v5
	v_lshl_add_u64 v[6:7], v[12:13], 0, v[0:1]
	global_store_dwordx4 v[6:7], v[2:5], off
	v_or_b32_e32 v6, 16, v14
	v_lshlrev_b32_e32 v0, 11, v6
	v_lshl_add_u64 v[2:3], v[10:11], 0, v[0:1]
	v_lshl_add_u32 v6, v6, 7, v17
	ds_read_b128 v[6:9], v6 offset:51200
	v_or_b32_e32 v18, 24, v14
	v_lshl_add_u64 v[14:15], v[12:13], 0, v[0:1]
	v_lshlrev_b32_e32 v0, 11, v18
	v_lshl_add_u64 v[10:11], v[10:11], 0, v[0:1]
	s_waitcnt lgkmcnt(0)
	v_lshlrev_b32_e32 v19, 16, v6
	v_and_b32_e32 v6, 0xffff0000, v6
	v_lshlrev_b32_e32 v20, 16, v7
	v_and_b32_e32 v7, 0xffff0000, v7
	v_lshlrev_b32_e32 v21, 16, v8
	v_and_b32_e32 v8, 0xffff0000, v8
	v_lshlrev_b32_e32 v22, 16, v9
	v_and_b32_e32 v9, 0xffff0000, v9
	s_waitcnt vmcnt(3)
	v_lshlrev_b32_e32 v23, 16, v108
	v_and_b32_e32 v2, 0xffff0000, v108
	v_lshlrev_b32_e32 v24, 16, v109
	v_and_b32_e32 v3, 0xffff0000, v109
	v_lshlrev_b32_e32 v25, 16, v110
	v_and_b32_e32 v4, 0xffff0000, v110
	v_lshlrev_b32_e32 v26, 16, v111
	v_and_b32_e32 v5, 0xffff0000, v111
	v_mul_f32_e32 v2, v2, v6
	v_mul_f32_e32 v3, v3, v7
	v_mul_f32_e32 v4, v4, v8
	v_mul_f32_e32 v5, v5, v9
	v_mul_f32_e32 v19, v23, v19
	v_mul_f32_e32 v6, v24, v20
	v_mul_f32_e32 v7, v25, v21
	v_mul_f32_e32 v8, v26, v22
	v_cvt_pk_bf16_f32 v2, v19, v2
	v_cvt_pk_bf16_f32 v3, v6, v3
	v_cvt_pk_bf16_f32 v4, v7, v4
	v_cvt_pk_bf16_f32 v5, v8, v5
	global_store_dwordx4 v[14:15], v[2:5], off
	v_lshl_add_u32 v6, v18, 7, v17
	ds_read_b128 v[6:9], v6 offset:51200
	s_waitcnt lgkmcnt(0)
	v_lshlrev_b32_e32 v10, 16, v6
	v_and_b32_e32 v6, 0xffff0000, v6
	v_lshlrev_b32_e32 v11, 16, v7
	v_and_b32_e32 v7, 0xffff0000, v7
	v_lshlrev_b32_e32 v14, 16, v8
	v_and_b32_e32 v8, 0xffff0000, v8
	v_lshlrev_b32_e32 v15, 16, v9
	v_and_b32_e32 v9, 0xffff0000, v9
	s_waitcnt vmcnt(3)
	v_lshlrev_b32_e32 v17, 16, v112
	v_and_b32_e32 v2, 0xffff0000, v112
	v_lshlrev_b32_e32 v18, 16, v113
	v_and_b32_e32 v3, 0xffff0000, v113
	v_lshlrev_b32_e32 v19, 16, v114
	v_and_b32_e32 v4, 0xffff0000, v114
	v_lshlrev_b32_e32 v20, 16, v115
	v_and_b32_e32 v5, 0xffff0000, v115
	v_mul_f32_e32 v2, v2, v6
	v_mul_f32_e32 v6, v18, v11
	v_mul_f32_e32 v3, v3, v7
	v_mul_f32_e32 v7, v19, v14
	v_mul_f32_e32 v4, v4, v8
	v_mul_f32_e32 v5, v5, v9
	v_cvt_pk_bf16_f32 v3, v6, v3
	v_cvt_pk_bf16_f32 v4, v7, v4
	v_lshl_add_u64 v[6:7], v[12:13], 0, v[0:1]
	v_mul_f32_e32 v10, v17, v10
	v_mul_f32_e32 v8, v20, v15
	v_cvt_pk_bf16_f32 v2, v10, v2
	v_cvt_pk_bf16_f32 v5, v8, v5
	global_store_dwordx4 v[6:7], v[2:5], off
	s_waitcnt lgkmcnt(0)
	s_barrier

; __device__ __forceinline__ int crow(int r,int hi){return (r&3)+8*(r>>2)+4*hi;}
;     ...
;   for(int r=0;r<16;++r)rli[r]=__builtin_amdgcn_rcpf(wsf[32+crow(r,hi)]);
;   if constexpr(DV2){ float*Orw=Oraw+(long)wid*QBLK*128;
;     #pragma unroll
;     for(int r=0;r<16;++r){const int orow=crow(r,hi);
;       #pragma unroll
;       for(int d0=0;d0<4;++d0) Orw[orow*128+d0*32+r32]=o[d0][r]*rli[r];}
;   } else {
;   bf16*Ow=OGu+(long)wid*QBLK*1024; const bf16*Zw=SZu+(long)wid*QBLK*1024;
;   { bf16*stg=(bf16*)(shm+LDS_OST)+wid*2048;
;     #pragma unroll
;     for(int r=0;r<16;++r){const int orow=crow(r,hi);
;       #pragma unroll
;       for(int d0=0;d0<2;++d0) stg[orow*64+d0*32+r32]=(bf16)(pk_bf16(o[d0][r]*rli[r],0.f)&0xffffu);}
;     asm volatile("s_waitcnt lgkmcnt(0)":::"memory");
;     #pragma unroll
;     for(int i=0;i<4;++i){const int row=i*8+(lane>>3),ch=lane&7; const u32x4 v=*(const u32x4*)(stg+row*64+ch*8); const u32x4 z=*(const u32x4*)(Zw+(long)row*1024+ch*8); u32x4 g;
.LBB0_837:
	s_or_b64 exec, exec, s[6:7]
	v_readlane_b32 s6, v254, 43
	s_or_b32 s6, s6, s22
	s_and_b64 s[4:5], s[4:5], exec
	v_readlane_b32 s4, v254, 42
	s_cselect_b32 s4, s6, s4
	v_readlane_b32 s36, v254, 25
	s_lshl_b32 s4, s4, 11
	v_readlane_b32 s42, v254, 31
	s_waitcnt lgkmcnt(0)
	v_readlane_b32 s43, v254, 32
	s_add_u32 s5, s42, s4
	ds_read_b128 v[4:7], v2 offset:49280
	ds_read_b128 v[8:11], v2 offset:49312
	s_addc_u32 s6, s43, 0
	s_lshl_b32 s7, s23, 7
	s_add_u32 s8, s5, s7
	v_readlane_b32 s44, v254, 33
	s_addc_u32 s9, s6, 0
	v_readlane_b32 s45, v254, 34
	s_add_u32 s4, s44, s4
	s_addc_u32 s5, s45, 0
	s_waitcnt lgkmcnt(1)
	v_rcp_f32_e32 v0, v4
	v_rcp_f32_e32 v3, v5
	v_rcp_f32_e32 v12, v6
	v_rcp_f32_e32 v13, v7
	s_waitcnt lgkmcnt(0)
	v_rcp_f32_e32 v14, v8
	ds_read_b128 v[4:7], v2 offset:49344
	v_rcp_f32_e32 v15, v9
	v_rcp_f32_e32 v50, v10
	v_rcp_f32_e32 v51, v11
	ds_read_b128 v[8:11], v2 offset:49376
	s_add_u32 s4, s4, s7
	s_addc_u32 s5, s5, 0
	s_lshl_b64 s[6:7], s[10:11], 16
	s_add_u32 s4, s4, s6
	s_addc_u32 s5, s5, s7
	s_lshl_b32 s10, s10, 12
	s_waitcnt lgkmcnt(1)
	v_rcp_f32_e32 v2, v4
	v_rcp_f32_e32 v4, v5
	v_rcp_f32_e32 v5, v6
	v_rcp_f32_e32 v6, v7
	s_waitcnt lgkmcnt(0)
	v_rcp_f32_e32 v7, v8
	v_rcp_f32_e32 v8, v9
	v_rcp_f32_e32 v9, v10
	v_rcp_f32_e32 v10, v11
	s_add_i32 s10, s10, 0
	v_lshlrev_b32_e32 v11, 9, v198
	v_lshlrev_b32_e32 v52, 1, v197
	v_mul_f32_e32 v34, v34, v0
	v_mul_f32_e32 v0, v18, v0
	v_add3_u32 v11, s10, v11, v52
	v_cvt_pk_bf16_f32 v0, v0, v1
	ds_write_b16 v11, v0 offset:51264
	v_mul_f32_e32 v0, v35, v3
	v_cvt_pk_bf16_f32 v0, v0, v1
	ds_write_b16 v11, v0 offset:51328
	v_mul_f32_e32 v0, v19, v3
	v_cvt_pk_bf16_f32 v0, v0, v1
	ds_write_b16 v11, v0 offset:51392
	v_mul_f32_e32 v0, v36, v12
	v_cvt_pk_bf16_f32 v0, v0, v1
	ds_write_b16 v11, v0 offset:51456
	v_mul_f32_e32 v0, v20, v12
	v_cvt_pk_bf16_f32 v0, v0, v1
	ds_write_b16 v11, v0 offset:51520
	v_mul_f32_e32 v0, v37, v13
	v_cvt_pk_bf16_f32 v0, v0, v1
	ds_write_b16 v11, v0 offset:51584
	v_mul_f32_e32 v0, v21, v13
	v_cvt_pk_bf16_f32 v0, v0, v1
	ds_write_b16 v11, v0 offset:51648
	v_mul_f32_e32 v0, v38, v14
	v_cvt_pk_bf16_f32 v0, v0, v1
	ds_write_b16 v11, v0 offset:52224
	v_mul_f32_e32 v0, v22, v14
	v_cvt_pk_bf16_f32 v0, v0, v1
	ds_write_b16 v11, v0 offset:52288
	v_mul_f32_e32 v0, v39, v15
	v_cvt_pk_bf16_f32 v0, v0, v1
	ds_write_b16 v11, v0 offset:52352
	v_mul_f32_e32 v0, v23, v15
	v_cvt_pk_bf16_f32 v0, v0, v1
	ds_write_b16 v11, v0 offset:52416
	v_mul_f32_e32 v0, v40, v50
	v_cvt_pk_bf16_f32 v0, v0, v1
	ds_write_b16 v11, v0 offset:52480
	v_mul_f32_e32 v0, v24, v50
	v_cvt_pk_bf16_f32 v0, v0, v1
	ds_write_b16 v11, v0 offset:52544
	v_mul_f32_e32 v0, v41, v51
	v_cvt_pk_bf16_f32 v0, v0, v1
	ds_write_b16 v11, v0 offset:52608
	v_mul_f32_e32 v0, v25, v51
	v_cvt_pk_bf16_f32 v0, v0, v1
	ds_write_b16 v11, v0 offset:52672
	v_mul_f32_e32 v0, v42, v2
	v_cvt_pk_bf16_f32 v0, v0, v1
	ds_write_b16 v11, v0 offset:53248
	v_mul_f32_e32 v0, v26, v2
	v_cvt_pk_bf16_f32 v0, v0, v1
	ds_write_b16 v11, v0 offset:53312
	v_mul_f32_e32 v0, v43, v4
	v_cvt_pk_bf16_f32 v0, v0, v1
	ds_write_b16 v11, v0 offset:53376
	v_mul_f32_e32 v0, v27, v4
	v_cvt_pk_bf16_f32 v0, v0, v1
	ds_write_b16 v11, v0 offset:53440
	v_mul_f32_e32 v0, v44, v5
	v_cvt_pk_bf16_f32 v0, v0, v1
	ds_write_b16 v11, v0 offset:53504
	v_mul_f32_e32 v0, v28, v5
	v_cvt_pk_bf16_f32 v0, v0, v1
	ds_write_b16 v11, v0 offset:53568
	v_mul_f32_e32 v0, v45, v6
	v_cvt_pk_bf16_f32 v0, v0, v1
	ds_write_b16 v11, v0 offset:53632
	v_mul_f32_e32 v0, v29, v6
	v_cvt_pk_bf16_f32 v0, v0, v1
	ds_write_b16 v11, v0 offset:53696
	v_mul_f32_e32 v0, v46, v7
	v_cvt_pk_bf16_f32 v0, v0, v1
	ds_write_b16 v11, v0 offset:54272
	v_mul_f32_e32 v0, v30, v7
	v_cvt_pk_bf16_f32 v0, v0, v1
	ds_write_b16 v11, v0 offset:54336
	v_mul_f32_e32 v0, v47, v8
	v_cvt_pk_bf16_f32 v0, v0, v1
	ds_write_b16 v11, v0 offset:54400
	v_mul_f32_e32 v0, v31, v8
	v_cvt_pk_bf16_f32 v0, v0, v1
	ds_write_b16 v11, v0 offset:54464
	v_mul_f32_e32 v0, v48, v9
	v_cvt_pk_bf16_f32 v0, v0, v1
	ds_write_b16 v11, v0 offset:54528
	v_mul_f32_e32 v0, v32, v9
	v_cvt_pk_bf16_f32 v0, v0, v1
	ds_write_b16 v11, v0 offset:54592
	v_mul_f32_e32 v0, v49, v10
	v_cvt_pk_bf16_f32 v0, v0, v1
	ds_write_b16 v11, v0 offset:54656
	v_mul_f32_e32 v0, v33, v10
	v_cvt_pk_bf16_f32 v0, v0, v1
	ds_write_b16 v11, v0 offset:54720
	s_add_u32 s6, s8, s6
	v_lshlrev_b32_e32 v0, 1, v196
	s_addc_u32 s7, s9, s7
	v_lshrrev_b32_e32 v14, 3, v17
	v_and_b32_e32 v0, 0x70, v0
	v_cvt_pk_bf16_f32 v34, v34, v1
	ds_write_b16 v11, v34 offset:51200
	v_add_u32_e32 v17, s10, v0
	v_lshl_add_u64 v[10:11], s[6:7], 0, v[0:1]
	v_lshl_add_u64 v[12:13], s[4:5], 0, v[0:1]
	v_mov_b32_e32 v67, 0
	v_lshlrev_b32_e32 v66, 11, v14
	v_lshl_add_u64 v[68:69], v[10:11], 0, v[66:67]
	global_load_dwordx4 v[50:53], v[68:69], off
	v_or_b32_e32 v66, 8, v14
	v_lshlrev_b32_e32 v66, 11, v66
	v_lshl_add_u64 v[68:69], v[10:11], 0, v[66:67]
	global_load_dwordx4 v[54:57], v[68:69], off
	v_or_b32_e32 v66, 16, v14
	v_lshlrev_b32_e32 v66, 11, v66
	v_lshl_add_u64 v[68:69], v[10:11], 0, v[66:67]
	global_load_dwordx4 v[58:61], v[68:69], off
	v_or_b32_e32 v66, 24, v14
	v_lshlrev_b32_e32 v66, 11, v66
	v_lshl_add_u64 v[68:69], v[10:11], 0, v[66:67]
	global_load_dwordx4 v[62:65], v[68:69], off
	v_lshlrev_b32_e32 v0, 11, v14
	s_waitcnt lgkmcnt(0)
;     ...
;     for(int i=0;i<4;++i){const int row=i*8+(lane>>3),ch=lane&7; const u32x4 v=*(const u32x4*)(stg+row*64+ch*8); const u32x4 z=*(const u32x4*)(Zw+(long)row*1024+ch*8); u32x4 g;
;       #pragma unroll
;       for(int e=0;e<4;++e){ const float a0=__uint_as_float(v[e]<<16)*__uint_as_float(z[e]<<16), a1=__uint_as_float(v[e]&0xffff0000u)*__uint_as_float(z[e]&0xffff0000u); g[e]=pk_bf16(a0,a1); }
;       *(u32x4*)(Ow+(long)row*1024+ch*8)=g;} }
;   }
;   asm volatile("s_waitcnt lgkmcnt(0)\n\ts_barrier":::"memory");
	v_lshl_add_u64 v[2:3], v[10:11], 0, v[0:1]
	v_lshl_add_u32 v6, v14, 7, v17
	ds_read_b128 v[6:9], v6 offset:51200
	v_readlane_b32 s4, v254, 4
	s_add_i32 s21, s21, s4
	v_readlane_b32 s37, v254, 26
	v_readlane_b32 s38, v254, 27
	s_waitcnt lgkmcnt(0)
	v_lshlrev_b32_e32 v15, 16, v6
	v_and_b32_e32 v6, 0xffff0000, v6
	v_readlane_b32 s39, v254, 28
	v_readlane_b32 s40, v254, 29
	v_readlane_b32 s41, v254, 30
	s_cmp_ge_u32 s21, s20
	v_readlane_b32 s46, v254, 35
	v_readlane_b32 s47, v254, 36
	v_readlane_b32 s48, v254, 37
	v_readlane_b32 s49, v254, 38
	v_readlane_b32 s50, v254, 39
	v_readlane_b32 s51, v254, 40
	s_waitcnt vmcnt(3)
	v_lshlrev_b32_e32 v18, 16, v50
	v_and_b32_e32 v2, 0xffff0000, v50
	v_mul_f32_e32 v15, v18, v15
	v_mul_f32_e32 v2, v2, v6
	v_cvt_pk_bf16_f32 v2, v15, v2
	v_lshlrev_b32_e32 v6, 16, v7
	v_lshlrev_b32_e32 v15, 16, v51
	v_and_b32_e32 v3, 0xffff0000, v51
	v_and_b32_e32 v7, 0xffff0000, v7
	v_mul_f32_e32 v6, v15, v6
	v_mul_f32_e32 v3, v3, v7
	v_cvt_pk_bf16_f32 v3, v6, v3
	v_lshlrev_b32_e32 v6, 16, v8
	v_lshlrev_b32_e32 v7, 16, v52
	v_mul_f32_e32 v6, v7, v6
	v_and_b32_e32 v4, 0xffff0000, v52
	v_and_b32_e32 v7, 0xffff0000, v8
	v_mul_f32_e32 v4, v4, v7
	v_cvt_pk_bf16_f32 v4, v6, v4
	v_lshlrev_b32_e32 v6, 16, v9
	v_lshlrev_b32_e32 v7, 16, v53
	v_mul_f32_e32 v6, v7, v6
	v_and_b32_e32 v5, 0xffff0000, v53
	v_and_b32_e32 v7, 0xffff0000, v9
	v_mul_f32_e32 v5, v5, v7
	v_cvt_pk_bf16_f32 v5, v6, v5
	v_lshl_add_u64 v[6:7], v[12:13], 0, v[0:1]
	global_store_dwordx4 v[6:7], v[2:5], off
	v_or_b32_e32 v6, 8, v14
	v_lshlrev_b32_e32 v0, 11, v6
	v_lshl_add_u64 v[2:3], v[10:11], 0, v[0:1]
	v_lshl_add_u32 v6, v6, 7, v17
	ds_read_b128 v[6:9], v6 offset:51200
	s_waitcnt lgkmcnt(0)
	v_lshlrev_b32_e32 v15, 16, v6
	v_and_b32_e32 v6, 0xffff0000, v6
	s_waitcnt vmcnt(3)
	v_lshlrev_b32_e32 v18, 16, v54
	v_and_b32_e32 v2, 0xffff0000, v54
	v_mul_f32_e32 v15, v18, v15
	v_mul_f32_e32 v2, v2, v6
	v_cvt_pk_bf16_f32 v2, v15, v2
	v_lshlrev_b32_e32 v6, 16, v7
	v_lshlrev_b32_e32 v15, 16, v55
	v_and_b32_e32 v3, 0xffff0000, v55
	v_and_b32_e32 v7, 0xffff0000, v7
	v_mul_f32_e32 v6, v15, v6
	v_mul_f32_e32 v3, v3, v7
	v_cvt_pk_bf16_f32 v3, v6, v3
	v_lshlrev_b32_e32 v6, 16, v8
	v_lshlrev_b32_e32 v7, 16, v56
	v_mul_f32_e32 v6, v7, v6
	v_and_b32_e32 v4, 0xffff0000, v56
	v_and_b32_e32 v7, 0xffff0000, v8
	v_mul_f32_e32 v4, v4, v7
	v_cvt_pk_bf16_f32 v4, v6, v4
	v_lshlrev_b32_e32 v6, 16, v9
	v_lshlrev_b32_e32 v7, 16, v57
	v_mul_f32_e32 v6, v7, v6
	v_and_b32_e32 v5, 0xffff0000, v57
	v_and_b32_e32 v7, 0xffff0000, v9
	v_mul_f32_e32 v5, v5, v7
	v_cvt_pk_bf16_f32 v5, v6, v5
	v_lshl_add_u64 v[6:7], v[12:13], 0, v[0:1]
	global_store_dwordx4 v[6:7], v[2:5], off
	v_or_b32_e32 v6, 16, v14
	v_lshlrev_b32_e32 v0, 11, v6
	v_lshl_add_u64 v[2:3], v[10:11], 0, v[0:1]
	v_lshl_add_u32 v6, v6, 7, v17
	ds_read_b128 v[6:9], v6 offset:51200
	v_or_b32_e32 v18, 24, v14
	v_lshl_add_u64 v[14:15], v[12:13], 0, v[0:1]
	v_lshlrev_b32_e32 v0, 11, v18
	v_lshl_add_u64 v[10:11], v[10:11], 0, v[0:1]
	s_waitcnt lgkmcnt(0)
	v_lshlrev_b32_e32 v19, 16, v6
	v_and_b32_e32 v6, 0xffff0000, v6
	v_lshlrev_b32_e32 v20, 16, v7
	v_and_b32_e32 v7, 0xffff0000, v7
	v_lshlrev_b32_e32 v21, 16, v8
	v_and_b32_e32 v8, 0xffff0000, v8
	v_lshlrev_b32_e32 v22, 16, v9
	v_and_b32_e32 v9, 0xffff0000, v9
	s_waitcnt vmcnt(3)
	v_lshlrev_b32_e32 v23, 16, v58
	v_and_b32_e32 v2, 0xffff0000, v58
	v_lshlrev_b32_e32 v24, 16, v59
	v_and_b32_e32 v3, 0xffff0000, v59
	v_lshlrev_b32_e32 v25, 16, v60
	v_and_b32_e32 v4, 0xffff0000, v60
	v_lshlrev_b32_e32 v26, 16, v61
	v_and_b32_e32 v5, 0xffff0000, v61
	v_mul_f32_e32 v2, v2, v6
	v_mul_f32_e32 v3, v3, v7
	v_mul_f32_e32 v4, v4, v8
	v_mul_f32_e32 v5, v5, v9
	v_mul_f32_e32 v19, v23, v19
	v_mul_f32_e32 v6, v24, v20
	v_mul_f32_e32 v7, v25, v21
	v_mul_f32_e32 v8, v26, v22
	v_cvt_pk_bf16_f32 v2, v19, v2
	v_cvt_pk_bf16_f32 v3, v6, v3
	v_cvt_pk_bf16_f32 v4, v7, v4
	v_cvt_pk_bf16_f32 v5, v8, v5
	global_store_dwordx4 v[14:15], v[2:5], off
	v_lshl_add_u32 v6, v18, 7, v17
	ds_read_b128 v[6:9], v6 offset:51200
	v_lshl_add_u64 v[10:11], v[12:13], 0, v[0:1]
	s_waitcnt lgkmcnt(0)
	v_lshlrev_b32_e32 v0, 16, v6
	v_and_b32_e32 v6, 0xffff0000, v6
	v_lshlrev_b32_e32 v12, 16, v7
	v_and_b32_e32 v7, 0xffff0000, v7
	v_lshlrev_b32_e32 v13, 16, v8
	v_and_b32_e32 v8, 0xffff0000, v8
	v_lshlrev_b32_e32 v14, 16, v9
	v_and_b32_e32 v9, 0xffff0000, v9
	s_waitcnt vmcnt(3)
	v_lshlrev_b32_e32 v15, 16, v62
	v_and_b32_e32 v2, 0xffff0000, v62
	v_lshlrev_b32_e32 v17, 16, v63
	v_and_b32_e32 v3, 0xffff0000, v63
	v_lshlrev_b32_e32 v18, 16, v64
	v_and_b32_e32 v4, 0xffff0000, v64
	v_lshlrev_b32_e32 v19, 16, v65
	v_and_b32_e32 v5, 0xffff0000, v65
	v_mul_f32_e32 v2, v2, v6
	v_mul_f32_e32 v3, v3, v7
	v_mul_f32_e32 v4, v4, v8
	v_mul_f32_e32 v5, v5, v9
	v_mul_f32_e32 v0, v15, v0
	v_mul_f32_e32 v6, v17, v12
	v_mul_f32_e32 v7, v18, v13
	v_mul_f32_e32 v8, v19, v14
	v_cvt_pk_bf16_f32 v2, v0, v2
	v_cvt_pk_bf16_f32 v3, v6, v3
	v_cvt_pk_bf16_f32 v4, v7, v4
	v_cvt_pk_bf16_f32 v5, v8, v5
	global_store_dwordx4 v[10:11], v[2:5], off
	s_waitcnt lgkmcnt(0)
	s_barrier
	s_cbranch_scc1 .LBB0_762

.LBB0_856:
	v_add_u32_e32 v14, s29, v204
	ds_read_b64_tr_b16 v[114:115], v14 offset:24576
	ds_read_b64_tr_b16 v[116:117], v14 offset:25088
	s_waitcnt lgkmcnt(9)
	v_mfma_f32_32x32x16_bf16 v[98:113], v[178:181], v[146:149], v[50:65]
	v_add_f32_e32 v2, v82, v83
	v_cvt_pk_bf16_f32 v134, v82, v83
	v_add_f32_e32 v2, v84, v2
	v_cvt_pk_bf16_f32 v135, v84, v85
	v_add_f32_e32 v2, v85, v2
	v_add_f32_e32 v2, v86, v2
	v_add_f32_e32 v2, v87, v2
	ds_read_b64_tr_b16 v[82:83], v14 offset:28672
	ds_read_b64_tr_b16 v[84:85], v14 offset:29184
	s_waitcnt lgkmcnt(10)
	v_mfma_f32_32x32x16_bf16 v[50:65], v[174:177], v[146:149], v[50:65]
	v_add_f32_e32 v2, v88, v2
	v_cvt_pk_bf16_f32 v136, v86, v87
	v_add_f32_e32 v2, v89, v2
	v_cvt_pk_bf16_f32 v137, v88, v89
	v_add_f32_e32 v2, v90, v2
	v_add_f32_e32 v2, v91, v2
	ds_read_b64_tr_b16 v[86:87], v14 offset:25600
	ds_read_b64_tr_b16 v[88:89], v14 offset:26112
	s_waitcnt lgkmcnt(11)
	v_mfma_f32_32x32x16_bf16 v[98:113], v[170:173], v[142:145], v[98:113]
	v_add_f32_e32 v2, v92, v2
	v_cvt_pk_bf16_f32 v10, v90, v91
	v_add_f32_e32 v2, v93, v2
	v_cvt_pk_bf16_f32 v11, v92, v93
	v_add_f32_e32 v2, v94, v2
	v_add_f32_e32 v2, v95, v2
	ds_read_b64_tr_b16 v[90:91], v14 offset:29696
	ds_read_b64_tr_b16 v[92:93], v14 offset:30208
	s_waitcnt lgkmcnt(12)
	v_mfma_f32_32x32x16_bf16 v[50:65], v[166:169], v[142:145], v[50:65]
	v_add_f32_e32 v2, v96, v2
	v_cvt_pk_bf16_f32 v12, v94, v95
	v_add_f32_e32 v2, v97, v2
	v_cvt_pk_bf16_f32 v13, v96, v97
	v_add_f32_e32 v2, v66, v2
	v_add_f32_e32 v2, v67, v2
	ds_read_b64_tr_b16 v[94:95], v14 offset:26624
	ds_read_b64_tr_b16 v[96:97], v14 offset:27136
	s_waitcnt lgkmcnt(13)
	v_mfma_f32_32x32x16_bf16 v[98:113], v[162:165], v[138:141], v[98:113]
	v_add_f32_e32 v2, v68, v2
	v_cvt_pk_bf16_f32 v6, v66, v67
	v_add_f32_e32 v2, v69, v2
	v_cvt_pk_bf16_f32 v7, v68, v69
	v_add_f32_e32 v2, v70, v2
	v_add_f32_e32 v2, v71, v2
	ds_read_b64_tr_b16 v[118:119], v14 offset:30720
	ds_read_b64_tr_b16 v[120:121], v14 offset:31232
	s_waitcnt lgkmcnt(14)
	v_mfma_f32_32x32x16_bf16 v[50:65], v[158:161], v[138:141], v[50:65]
	v_add_f32_e32 v2, v72, v2
	v_cvt_pk_bf16_f32 v8, v70, v71
	v_add_f32_e32 v2, v73, v2
	v_cvt_pk_bf16_f32 v9, v72, v73
	v_add_f32_e32 v2, v74, v2
	v_add_f32_e32 v2, v75, v2
	ds_read_b64_tr_b16 v[122:123], v14 offset:27648
	ds_read_b64_tr_b16 v[124:125], v14 offset:28160
	s_waitcnt lgkmcnt(14)
	v_mfma_f32_32x32x16_bf16 v[98:113], v[154:157], v[130:133], v[98:113]
	v_add_f32_e32 v2, v76, v2
	v_cvt_pk_bf16_f32 v3, v76, v77
	v_add_f32_e32 v2, v77, v2
	v_add_f32_e32 v2, v78, v2
	v_add_f32_e32 v15, v79, v2
	v_cvt_pk_bf16_f32 v2, v74, v75
	ds_read_b64_tr_b16 v[126:127], v14 offset:31744
	ds_read_b64_tr_b16 v[128:129], v14 offset:32256
	v_mfma_f32_32x32x16_bf16 v[50:65], v[150:153], v[130:133], v[50:65]
	v_add_f32_e32 v4, v80, v15
	v_cvt_pk_bf16_f32 v5, v80, v81
	v_add_f32_e32 v4, v81, v4
	v_add_f32_e32 v14, 0, v4
	v_cvt_pk_bf16_f32 v4, v78, v79
	v_max_f32_e32 v15, v99, v99
	v_max_f32_e32 v66, v98, v98
	v_max_f32_e32 v15, v66, v15
	s_nop 3
	v_max3_f32 v66, v100, v101, v51
	v_max3_f32 v15, v15, v50, v52
	v_max3_f32 v15, v15, v53, v102
	v_max3_f32 v66, v66, v104, v105
	v_max3_f32 v15, v15, v103, v54
	v_max3_f32 v66, v66, v56, v57
	v_max3_f32 v15, v15, v55, v106
	v_max3_f32 v66, v66, v108, v109
	v_max3_f32 v15, v15, v107, v58
	v_max3_f32 v66, v66, v60, v61
	v_max3_f32 v15, v15, v59, v110
	v_max3_f32 v66, v66, v112, v113
	v_max3_f32 v15, v15, v111, v62
	v_max3_f32 v66, v66, v64, v65
	v_max3_f32 v15, v15, v63, v66
	v_mov_b32_e32 v66, v15
	s_nop 1
	v_permlane32_swap_b32_e32 v15, v66
	v_max_f32_e32 v66, v66, v66
	v_max_f32_e32 v15, v15, v15
	v_max_f32_e32 v15, v15, v66
	v_cmp_lt_f32_e32 vcc, s84, v15
	s_cmp_lg_u64 vcc, 0
	v_add_f32_e32 v14, v206, v14
	s_cselect_b64 s[6:7], -1, 0
	s_cbranch_vccnz .LBB0_907

.LBB0_863:
	v_add_u32_e32 v186, s14, v204
	ds_read_b64_tr_b16 v[182:183], v186 offset:24576
	ds_read_b64_tr_b16 v[184:185], v186 offset:25088
	s_waitcnt lgkmcnt(9)
	v_mfma_f32_32x32x16_bf16 v[114:129], v[178:181], v[146:149], v[50:65]
	v_add_f32_e32 v2, v82, v83
	v_cvt_pk_bf16_f32 v134, v82, v83
	v_add_f32_e32 v2, v84, v2
	v_cvt_pk_bf16_f32 v135, v84, v85
	v_add_f32_e32 v2, v85, v2
	v_add_f32_e32 v2, v86, v2
	v_add_f32_e32 v2, v87, v2
	ds_read_b64_tr_b16 v[178:179], v186 offset:28672
	ds_read_b64_tr_b16 v[180:181], v186 offset:29184
	s_waitcnt lgkmcnt(10)
	v_mfma_f32_32x32x16_bf16 v[98:113], v[174:177], v[146:149], v[50:65]
	v_add_f32_e32 v2, v88, v2
	v_cvt_pk_bf16_f32 v136, v86, v87
	v_add_f32_e32 v2, v89, v2
	v_cvt_pk_bf16_f32 v137, v88, v89
	v_add_f32_e32 v2, v90, v2
	v_add_f32_e32 v2, v91, v2
	ds_read_b64_tr_b16 v[82:83], v186 offset:25600
	ds_read_b64_tr_b16 v[84:85], v186 offset:26112
	s_waitcnt lgkmcnt(11)
	v_mfma_f32_32x32x16_bf16 v[114:129], v[170:173], v[142:145], v[114:129]
	v_add_f32_e32 v2, v92, v2
	v_cvt_pk_bf16_f32 v10, v90, v91
	v_add_f32_e32 v2, v93, v2
	v_cvt_pk_bf16_f32 v11, v92, v93
	v_add_f32_e32 v2, v94, v2
	v_add_f32_e32 v2, v95, v2
	ds_read_b64_tr_b16 v[86:87], v186 offset:29696
	ds_read_b64_tr_b16 v[88:89], v186 offset:30208
	s_waitcnt lgkmcnt(12)
	v_mfma_f32_32x32x16_bf16 v[98:113], v[166:169], v[142:145], v[98:113]
	v_add_f32_e32 v2, v96, v2
	v_cvt_pk_bf16_f32 v12, v94, v95
	v_add_f32_e32 v2, v97, v2
	v_cvt_pk_bf16_f32 v13, v96, v97
	v_add_f32_e32 v2, v66, v2
	v_add_f32_e32 v2, v67, v2
	ds_read_b64_tr_b16 v[90:91], v186 offset:26624
	ds_read_b64_tr_b16 v[92:93], v186 offset:27136
	s_waitcnt lgkmcnt(13)
	v_mfma_f32_32x32x16_bf16 v[114:129], v[162:165], v[138:141], v[114:129]
	v_add_f32_e32 v2, v68, v2
	v_cvt_pk_bf16_f32 v6, v66, v67
	v_add_f32_e32 v2, v69, v2
	v_cvt_pk_bf16_f32 v7, v68, v69
	v_add_f32_e32 v2, v70, v2
	v_add_f32_e32 v2, v71, v2
	ds_read_b64_tr_b16 v[66:67], v186 offset:30720
	ds_read_b64_tr_b16 v[68:69], v186 offset:31232
	s_waitcnt lgkmcnt(14)
	v_mfma_f32_32x32x16_bf16 v[98:113], v[158:161], v[138:141], v[98:113]
	v_add_f32_e32 v2, v72, v2
	v_cvt_pk_bf16_f32 v8, v70, v71
	v_add_f32_e32 v2, v73, v2
	v_cvt_pk_bf16_f32 v9, v72, v73
	v_add_f32_e32 v2, v74, v2
	v_add_f32_e32 v2, v75, v2
	ds_read_b64_tr_b16 v[70:71], v186 offset:27648
	ds_read_b64_tr_b16 v[72:73], v186 offset:28160
	s_waitcnt lgkmcnt(14)
	v_mfma_f32_32x32x16_bf16 v[114:129], v[154:157], v[130:133], v[114:129]
	v_add_f32_e32 v2, v76, v2
	v_cvt_pk_bf16_f32 v3, v76, v77
	v_add_f32_e32 v2, v77, v2
	v_add_f32_e32 v2, v78, v2
	v_add_f32_e32 v94, v79, v2
	v_cvt_pk_bf16_f32 v2, v74, v75
	ds_read_b64_tr_b16 v[74:75], v186 offset:31744
	ds_read_b64_tr_b16 v[76:77], v186 offset:32256
	v_mfma_f32_32x32x16_bf16 v[98:113], v[150:153], v[130:133], v[98:113]
	v_add_f32_e32 v4, v80, v94
	v_cvt_pk_bf16_f32 v5, v80, v81
	v_add_f32_e32 v4, v81, v4
	v_add_f32_e32 v94, 0, v4
	v_cvt_pk_bf16_f32 v4, v78, v79
	s_add_i32 s8, s16, 1
	s_cmp_ge_u32 s8, s25
	s_cselect_b64 s[12:13], -1, 0
	s_and_b64 vcc, exec, s[12:13]
	s_cbranch_vccnz .LBB0_865
	s_add_i32 s8, s28, s26
	v_lshl_add_u64 v[78:79], v[194:195], 0, s[52:53]
	s_mov_b32 s9, m0
	s_mov_b32 m0, s8
	s_nop 0
	global_load_lds_dwordx4 v[78:79], off
	s_mov_b32 m0, s9

.LBB0_874:
	v_add_u32_e32 v208, s28, v204
	ds_read_b64_tr_b16 v[190:191], v208 offset:24576
	ds_read_b64_tr_b16 v[192:193], v208 offset:25088
	s_waitcnt lgkmcnt(9)
	v_mfma_f32_32x32x16_bf16 v[82:97], v[178:181], v[146:149], v[50:65]
	v_add_f32_e32 v2, v114, v115
	v_cvt_pk_bf16_f32 v134, v114, v115
	v_add_f32_e32 v2, v116, v2
	v_cvt_pk_bf16_f32 v135, v116, v117
	v_add_f32_e32 v2, v117, v2
	v_add_f32_e32 v2, v118, v2
	v_add_f32_e32 v2, v119, v2
	ds_read_b64_tr_b16 v[186:187], v208 offset:28672
	ds_read_b64_tr_b16 v[188:189], v208 offset:29184
	s_waitcnt lgkmcnt(10)
	v_mfma_f32_32x32x16_bf16 v[66:81], v[174:177], v[146:149], v[50:65]
	v_add_f32_e32 v2, v120, v2
	v_cvt_pk_bf16_f32 v136, v118, v119
	v_add_f32_e32 v2, v121, v2
	v_cvt_pk_bf16_f32 v137, v120, v121
	v_add_f32_e32 v2, v122, v2
	v_add_f32_e32 v2, v123, v2
	ds_read_b64_tr_b16 v[182:183], v208 offset:25600
	ds_read_b64_tr_b16 v[184:185], v208 offset:26112
	s_waitcnt lgkmcnt(11)
	v_mfma_f32_32x32x16_bf16 v[82:97], v[170:173], v[142:145], v[82:97]
	v_add_f32_e32 v2, v124, v2
	v_cvt_pk_bf16_f32 v10, v122, v123
	v_add_f32_e32 v2, v125, v2
	v_cvt_pk_bf16_f32 v11, v124, v125
	v_add_f32_e32 v2, v126, v2
	v_add_f32_e32 v2, v127, v2
	ds_read_b64_tr_b16 v[122:123], v208 offset:29696
	ds_read_b64_tr_b16 v[124:125], v208 offset:30208
	s_waitcnt lgkmcnt(12)
	v_mfma_f32_32x32x16_bf16 v[66:81], v[166:169], v[142:145], v[66:81]
	v_add_f32_e32 v2, v128, v2
	v_cvt_pk_bf16_f32 v12, v126, v127
	v_add_f32_e32 v2, v129, v2
	v_cvt_pk_bf16_f32 v13, v128, v129
	v_add_f32_e32 v2, v98, v2
	v_add_f32_e32 v2, v99, v2
	ds_read_b64_tr_b16 v[118:119], v208 offset:26624
	ds_read_b64_tr_b16 v[120:121], v208 offset:27136
	s_waitcnt lgkmcnt(13)
	v_mfma_f32_32x32x16_bf16 v[82:97], v[162:165], v[138:141], v[82:97]
	v_add_f32_e32 v2, v100, v2
	v_cvt_pk_bf16_f32 v6, v98, v99
	v_add_f32_e32 v2, v101, v2
	v_cvt_pk_bf16_f32 v7, v100, v101
	v_add_f32_e32 v2, v102, v2
	v_add_f32_e32 v2, v103, v2
	ds_read_b64_tr_b16 v[114:115], v208 offset:30720
	ds_read_b64_tr_b16 v[116:117], v208 offset:31232
	s_waitcnt lgkmcnt(14)
	v_mfma_f32_32x32x16_bf16 v[66:81], v[158:161], v[138:141], v[66:81]
	v_add_f32_e32 v2, v104, v2
	v_cvt_pk_bf16_f32 v8, v102, v103
	v_add_f32_e32 v2, v105, v2
	v_cvt_pk_bf16_f32 v9, v104, v105
	v_add_f32_e32 v2, v106, v2
	v_add_f32_e32 v2, v107, v2
	ds_read_b64_tr_b16 v[102:103], v208 offset:27648
	ds_read_b64_tr_b16 v[104:105], v208 offset:28160
	s_waitcnt lgkmcnt(14)
	v_mfma_f32_32x32x16_bf16 v[82:97], v[154:157], v[130:133], v[82:97]
	v_add_f32_e32 v2, v108, v2
	v_cvt_pk_bf16_f32 v3, v108, v109
	v_add_f32_e32 v2, v109, v2
	v_add_f32_e32 v2, v110, v2
	v_add_f32_e32 v126, v111, v2
	v_cvt_pk_bf16_f32 v2, v106, v107
	ds_read_b64_tr_b16 v[98:99], v208 offset:31744
	ds_read_b64_tr_b16 v[100:101], v208 offset:32256
	v_mfma_f32_32x32x16_bf16 v[66:81], v[150:153], v[130:133], v[66:81]
	v_add_f32_e32 v4, v112, v126
	v_cvt_pk_bf16_f32 v5, v112, v113
	v_add_f32_e32 v4, v113, v4
	v_add_f32_e32 v106, 0, v4
	v_cvt_pk_bf16_f32 v4, v110, v111
	s_add_i32 s31, s16, 2
	s_cmp_ge_u32 s31, s25
	s_cselect_b64 s[14:15], -1, 0
	s_and_b64 vcc, exec, s[14:15]
	s_cbranch_vccnz .LBB0_876
	s_add_i32 s8, s29, s26
	s_mov_b32 s9, m0
	s_mov_b32 m0, s8
	s_nop 0
	global_load_lds_dwordx4 v[194:195], off
	s_mov_b32 m0, s9
